# GEMM K-loops without the per-MMA s_setprio toggles
# speedup vs baseline: 1.0020x; 1.0018x over previous
.LBB0_225:
	ds_read_b128 v[132:135], v142
	ds_read_b128 v[136:139], v142 offset:1024
	ds_read_b128 v[150:153], v142 offset:2048
	ds_read_b128 v[154:157], v142 offset:3072
	s_add_i32 s69, s8, s68
	s_add_i32 s70, s69, 0x80080
	s_mov_b32 m0, s7
	ds_read_b128 v[158:161], v143
	ds_read_b128 v[162:165], v143 offset:1024
	ds_read_b128 v[166:169], v144
	ds_read_b128 v[170:173], v144 offset:1024
	ds_read_b128 v[178:181], v145
	ds_read_b128 v[214:217], v145 offset:1024
	ds_read_b128 v[218:221], v146
	ds_read_b128 v[222:225], v146 offset:1024
	buffer_load_dwordx4 v140, s[48:51], s70 offen lds
	s_mov_b32 m0, s6
	s_nop 0
	buffer_load_dwordx4 v141, s[48:51], s70 offen lds
	s_waitcnt lgkmcnt(8)
	s_barrier
	s_waitcnt lgkmcnt(0)
	s_waitcnt lgkmcnt(0)
	v_mfma_f32_16x16x32_bf16 v[126:129], v[132:135], v[158:161], v[126:129]
	v_mfma_f32_16x16x32_bf16 v[122:125], v[150:153], v[158:161], v[122:125]
	v_mfma_f32_16x16x32_bf16 v[118:121], v[132:135], v[166:169], v[118:121]
	v_mfma_f32_16x16x32_bf16 v[114:117], v[150:153], v[166:169], v[114:117]
	v_mfma_f32_16x16x32_bf16 v[110:113], v[132:135], v[178:181], v[110:113]
	v_mfma_f32_16x16x32_bf16 v[106:109], v[150:153], v[178:181], v[106:109]
	v_mfma_f32_16x16x32_bf16 v[102:105], v[132:135], v[218:221], v[102:105]
	v_mfma_f32_16x16x32_bf16 v[98:101], v[150:153], v[218:221], v[98:101]
	v_mfma_f32_16x16x32_bf16 v[126:129], v[136:139], v[162:165], v[126:129]
	v_mfma_f32_16x16x32_bf16 v[122:125], v[154:157], v[162:165], v[122:125]
	v_mfma_f32_16x16x32_bf16 v[118:121], v[136:139], v[170:173], v[118:121]
	v_mfma_f32_16x16x32_bf16 v[114:117], v[154:157], v[170:173], v[114:117]
	v_mfma_f32_16x16x32_bf16 v[110:113], v[136:139], v[214:217], v[110:113]
	v_mfma_f32_16x16x32_bf16 v[106:109], v[154:157], v[214:217], v[106:109]
	v_mfma_f32_16x16x32_bf16 v[102:105], v[136:139], v[222:225], v[102:105]
	v_mfma_f32_16x16x32_bf16 v[98:101], v[154:157], v[222:225], v[98:101]
	s_barrier
	s_add_i32 s70, s9, s68
	s_add_i32 s71, s70, 0x100
	s_mov_b32 m0, s28
	ds_read_b128 v[226:229], v147
	ds_read_b128 v[230:233], v147 offset:1024
	ds_read_b128 v[234:237], v147 offset:2048
	ds_read_b128 v[238:241], v147 offset:3072
	buffer_load_dwordx4 v140, s[44:47], s71 offen lds
	s_mov_b32 m0, s29
	s_nop 0
	buffer_load_dwordx4 v141, s[44:47], s71 offen lds
	s_barrier
	s_waitcnt lgkmcnt(0)
	s_waitcnt lgkmcnt(0)
	v_mfma_f32_16x16x32_bf16 v[94:97], v[226:229], v[158:161], v[94:97]
	v_mfma_f32_16x16x32_bf16 v[90:93], v[234:237], v[158:161], v[90:93]
	v_mfma_f32_16x16x32_bf16 v[86:89], v[226:229], v[166:169], v[86:89]
	v_mfma_f32_16x16x32_bf16 v[82:85], v[234:237], v[166:169], v[82:85]
	v_mfma_f32_16x16x32_bf16 v[78:81], v[226:229], v[178:181], v[78:81]
	v_mfma_f32_16x16x32_bf16 v[74:77], v[234:237], v[178:181], v[74:77]
	v_mfma_f32_16x16x32_bf16 v[70:73], v[226:229], v[218:221], v[70:73]
	v_mfma_f32_16x16x32_bf16 v[66:69], v[234:237], v[218:221], v[66:69]
	v_mfma_f32_16x16x32_bf16 v[94:97], v[230:233], v[162:165], v[94:97]
	v_mfma_f32_16x16x32_bf16 v[90:93], v[238:241], v[162:165], v[90:93]
	v_mfma_f32_16x16x32_bf16 v[86:89], v[230:233], v[170:173], v[86:89]
	v_mfma_f32_16x16x32_bf16 v[82:85], v[238:241], v[170:173], v[82:85]
	v_mfma_f32_16x16x32_bf16 v[78:81], v[230:233], v[214:217], v[78:81]
	v_mfma_f32_16x16x32_bf16 v[74:77], v[238:241], v[214:217], v[74:77]
	v_mfma_f32_16x16x32_bf16 v[70:73], v[230:233], v[222:225], v[70:73]
	v_mfma_f32_16x16x32_bf16 v[66:69], v[238:241], v[222:225], v[66:69]
	s_add_i32 s71, s69, 0x100
	s_mov_b32 m0, s27
	s_barrier
	ds_read_b128 v[158:161], v143 offset:16384
	ds_read_b128 v[162:165], v143 offset:17408
	ds_read_b128 v[166:169], v144 offset:16384
	ds_read_b128 v[170:173], v144 offset:17408
	ds_read_b128 v[178:181], v145 offset:16384
	ds_read_b128 v[214:217], v145 offset:17408
	ds_read_b128 v[218:221], v146 offset:16384
	ds_read_b128 v[222:225], v146 offset:17408
	buffer_load_dwordx4 v140, s[48:51], s71 offen lds
	s_mov_b32 m0, s30
	s_nop 0
	buffer_load_dwordx4 v141, s[48:51], s71 offen lds
	s_barrier
	s_waitcnt lgkmcnt(0)
	s_waitcnt lgkmcnt(0)
	v_mfma_f32_16x16x32_bf16 v[62:65], v[132:135], v[158:161], v[62:65]
	v_mfma_f32_16x16x32_bf16 v[58:61], v[150:153], v[158:161], v[58:61]
	v_mfma_f32_16x16x32_bf16 v[54:57], v[132:135], v[166:169], v[54:57]
	v_mfma_f32_16x16x32_bf16 v[50:53], v[150:153], v[166:169], v[50:53]
	v_mfma_f32_16x16x32_bf16 v[46:49], v[132:135], v[178:181], v[46:49]
	v_mfma_f32_16x16x32_bf16 v[42:45], v[150:153], v[178:181], v[42:45]
	v_mfma_f32_16x16x32_bf16 v[38:41], v[132:135], v[218:221], v[38:41]
	v_mfma_f32_16x16x32_bf16 v[34:37], v[150:153], v[218:221], v[34:37]
	v_mfma_f32_16x16x32_bf16 v[62:65], v[136:139], v[162:165], v[62:65]
	v_mfma_f32_16x16x32_bf16 v[58:61], v[154:157], v[162:165], v[58:61]
	v_mfma_f32_16x16x32_bf16 v[54:57], v[136:139], v[170:173], v[54:57]
	v_mfma_f32_16x16x32_bf16 v[50:53], v[154:157], v[170:173], v[50:53]
	v_mfma_f32_16x16x32_bf16 v[46:49], v[136:139], v[214:217], v[46:49]
	v_mfma_f32_16x16x32_bf16 v[42:45], v[154:157], v[214:217], v[42:45]
	v_mfma_f32_16x16x32_bf16 v[38:41], v[136:139], v[222:225], v[38:41]
	v_mfma_f32_16x16x32_bf16 v[34:37], v[154:157], v[222:225], v[34:37]
	s_barrier
	s_add_i32 s71, s70, 0x80100
	s_mov_b32 m0, s31
	s_nop 0
	buffer_load_dwordx4 v140, s[44:47], s71 offen lds
	s_mov_b32 m0, s34
	s_nop 0
	buffer_load_dwordx4 v141, s[44:47], s71 offen lds
	s_waitcnt vmcnt(6)
	s_barrier
	v_mfma_f32_16x16x32_bf16 v[30:33], v[226:229], v[158:161], v[30:33]
	v_mfma_f32_16x16x32_bf16 v[26:29], v[234:237], v[158:161], v[26:29]
	v_mfma_f32_16x16x32_bf16 v[22:25], v[226:229], v[166:169], v[22:25]
	v_mfma_f32_16x16x32_bf16 v[18:21], v[234:237], v[166:169], v[18:21]
	v_mfma_f32_16x16x32_bf16 v[12:15], v[226:229], v[178:181], v[12:15]
	v_mfma_f32_16x16x32_bf16 v[8:11], v[234:237], v[178:181], v[8:11]
	v_mfma_f32_16x16x32_bf16 v[4:7], v[226:229], v[218:221], v[4:7]
	v_mfma_f32_16x16x32_bf16 v[0:3], v[234:237], v[218:221], v[0:3]
	v_mfma_f32_16x16x32_bf16 v[30:33], v[230:233], v[162:165], v[30:33]
	v_mfma_f32_16x16x32_bf16 v[26:29], v[238:241], v[162:165], v[26:29]
	v_mfma_f32_16x16x32_bf16 v[22:25], v[230:233], v[170:173], v[22:25]
	v_mfma_f32_16x16x32_bf16 v[18:21], v[238:241], v[170:173], v[18:21]
	v_mfma_f32_16x16x32_bf16 v[12:15], v[230:233], v[214:217], v[12:15]
	v_mfma_f32_16x16x32_bf16 v[8:11], v[238:241], v[214:217], v[8:11]
	v_mfma_f32_16x16x32_bf16 v[4:7], v[230:233], v[222:225], v[4:7]
	v_mfma_f32_16x16x32_bf16 v[0:3], v[238:241], v[222:225], v[0:3]
	s_barrier
	ds_read_b128 v[132:135], v148
	ds_read_b128 v[136:139], v148 offset:1024
	ds_read_b128 v[150:153], v148 offset:2048
	ds_read_b128 v[154:157], v148 offset:3072
	s_add_i32 s71, s69, 0x80100
	s_mov_b32 m0, s35
	ds_read_b128 v[158:161], v143 offset:32768
	ds_read_b128 v[162:165], v143 offset:33792
	ds_read_b128 v[166:169], v144 offset:32768
	ds_read_b128 v[170:173], v144 offset:33792
	ds_read_b128 v[178:181], v145 offset:32768
	ds_read_b128 v[214:217], v145 offset:33792
	ds_read_b128 v[218:221], v146 offset:32768
	ds_read_b128 v[222:225], v146 offset:33792
	buffer_load_dwordx4 v140, s[48:51], s71 offen lds
	s_mov_b32 m0, s36
	s_nop 0
	buffer_load_dwordx4 v141, s[48:51], s71 offen lds
	s_waitcnt lgkmcnt(8)
	s_barrier
	s_waitcnt lgkmcnt(0)
	s_waitcnt lgkmcnt(0)
	v_mfma_f32_16x16x32_bf16 v[126:129], v[132:135], v[158:161], v[126:129]
	v_mfma_f32_16x16x32_bf16 v[122:125], v[150:153], v[158:161], v[122:125]
	v_mfma_f32_16x16x32_bf16 v[118:121], v[132:135], v[166:169], v[118:121]
	v_mfma_f32_16x16x32_bf16 v[114:117], v[150:153], v[166:169], v[114:117]
	v_mfma_f32_16x16x32_bf16 v[110:113], v[132:135], v[178:181], v[110:113]
	v_mfma_f32_16x16x32_bf16 v[106:109], v[150:153], v[178:181], v[106:109]
	v_mfma_f32_16x16x32_bf16 v[102:105], v[132:135], v[218:221], v[102:105]
	v_mfma_f32_16x16x32_bf16 v[98:101], v[150:153], v[218:221], v[98:101]
	v_mfma_f32_16x16x32_bf16 v[126:129], v[136:139], v[162:165], v[126:129]
	v_mfma_f32_16x16x32_bf16 v[122:125], v[154:157], v[162:165], v[122:125]
	v_mfma_f32_16x16x32_bf16 v[118:121], v[136:139], v[170:173], v[118:121]
	v_mfma_f32_16x16x32_bf16 v[114:117], v[154:157], v[170:173], v[114:117]
	v_mfma_f32_16x16x32_bf16 v[110:113], v[136:139], v[214:217], v[110:113]
	v_mfma_f32_16x16x32_bf16 v[106:109], v[154:157], v[214:217], v[106:109]
	v_mfma_f32_16x16x32_bf16 v[102:105], v[136:139], v[222:225], v[102:105]
	v_mfma_f32_16x16x32_bf16 v[98:101], v[154:157], v[222:225], v[98:101]
	s_barrier
	s_add_i32 s71, s70, 0x180
	s_mov_b32 m0, s37
	ds_read_b128 v[226:229], v149
	ds_read_b128 v[230:233], v149 offset:1024
	ds_read_b128 v[234:237], v149 offset:2048
	ds_read_b128 v[238:241], v149 offset:3072
	buffer_load_dwordx4 v140, s[44:47], s71 offen lds
	s_mov_b32 m0, s38
	s_nop 0
	buffer_load_dwordx4 v141, s[44:47], s71 offen lds
	s_barrier
	s_waitcnt lgkmcnt(0)
	s_waitcnt lgkmcnt(0)
	v_mfma_f32_16x16x32_bf16 v[94:97], v[226:229], v[158:161], v[94:97]
	v_mfma_f32_16x16x32_bf16 v[90:93], v[234:237], v[158:161], v[90:93]
	v_mfma_f32_16x16x32_bf16 v[86:89], v[226:229], v[166:169], v[86:89]
	v_mfma_f32_16x16x32_bf16 v[82:85], v[234:237], v[166:169], v[82:85]
	v_mfma_f32_16x16x32_bf16 v[78:81], v[226:229], v[178:181], v[78:81]
	v_mfma_f32_16x16x32_bf16 v[74:77], v[234:237], v[178:181], v[74:77]
	v_mfma_f32_16x16x32_bf16 v[70:73], v[226:229], v[218:221], v[70:73]
	v_mfma_f32_16x16x32_bf16 v[66:69], v[234:237], v[218:221], v[66:69]
	v_mfma_f32_16x16x32_bf16 v[94:97], v[230:233], v[162:165], v[94:97]
	v_mfma_f32_16x16x32_bf16 v[90:93], v[238:241], v[162:165], v[90:93]
	v_mfma_f32_16x16x32_bf16 v[86:89], v[230:233], v[170:173], v[86:89]
	v_mfma_f32_16x16x32_bf16 v[82:85], v[238:241], v[170:173], v[82:85]
	v_mfma_f32_16x16x32_bf16 v[78:81], v[230:233], v[214:217], v[78:81]
	v_mfma_f32_16x16x32_bf16 v[74:77], v[238:241], v[214:217], v[74:77]
	v_mfma_f32_16x16x32_bf16 v[70:73], v[230:233], v[222:225], v[70:73]
	v_mfma_f32_16x16x32_bf16 v[66:69], v[238:241], v[222:225], v[66:69]
	s_addk_i32 s69, 0x180
	s_mov_b32 m0, s39
	s_barrier
	ds_read_b128 v[158:161], v143 offset:49152
	ds_read_b128 v[162:165], v143 offset:50176
	ds_read_b128 v[166:169], v144 offset:49152
	ds_read_b128 v[170:173], v144 offset:50176
	ds_read_b128 v[178:181], v145 offset:49152
	ds_read_b128 v[214:217], v145 offset:50176
	ds_read_b128 v[218:221], v146 offset:49152
	ds_read_b128 v[222:225], v146 offset:50176
	buffer_load_dwordx4 v140, s[48:51], s69 offen lds
	s_mov_b32 m0, s62
	s_nop 0
	buffer_load_dwordx4 v141, s[48:51], s69 offen lds
	s_barrier
	s_waitcnt lgkmcnt(0)
	s_waitcnt lgkmcnt(0)
	v_mfma_f32_16x16x32_bf16 v[62:65], v[132:135], v[158:161], v[62:65]
	v_mfma_f32_16x16x32_bf16 v[58:61], v[150:153], v[158:161], v[58:61]
	v_mfma_f32_16x16x32_bf16 v[54:57], v[132:135], v[166:169], v[54:57]
	v_mfma_f32_16x16x32_bf16 v[50:53], v[150:153], v[166:169], v[50:53]
	v_mfma_f32_16x16x32_bf16 v[46:49], v[132:135], v[178:181], v[46:49]
	v_mfma_f32_16x16x32_bf16 v[42:45], v[150:153], v[178:181], v[42:45]
	v_mfma_f32_16x16x32_bf16 v[38:41], v[132:135], v[218:221], v[38:41]
	v_mfma_f32_16x16x32_bf16 v[34:37], v[150:153], v[218:221], v[34:37]
	v_mfma_f32_16x16x32_bf16 v[62:65], v[136:139], v[162:165], v[62:65]
	v_mfma_f32_16x16x32_bf16 v[58:61], v[154:157], v[162:165], v[58:61]
	v_mfma_f32_16x16x32_bf16 v[54:57], v[136:139], v[170:173], v[54:57]
	v_mfma_f32_16x16x32_bf16 v[50:53], v[154:157], v[170:173], v[50:53]
	v_mfma_f32_16x16x32_bf16 v[46:49], v[136:139], v[214:217], v[46:49]
	v_mfma_f32_16x16x32_bf16 v[42:45], v[154:157], v[214:217], v[42:45]
	v_mfma_f32_16x16x32_bf16 v[38:41], v[136:139], v[222:225], v[38:41]
	v_mfma_f32_16x16x32_bf16 v[34:37], v[154:157], v[222:225], v[34:37]
	s_barrier
	s_add_i32 s70, s70, 0x80180
	s_mov_b32 m0, s63
	s_nop 0
	buffer_load_dwordx4 v140, s[44:47], s70 offen lds
	s_mov_b32 m0, s66
	s_nop 0
	buffer_load_dwordx4 v141, s[44:47], s70 offen lds
	s_waitcnt vmcnt(6)
	s_barrier
	v_mfma_f32_16x16x32_bf16 v[30:33], v[226:229], v[158:161], v[30:33]
	v_mfma_f32_16x16x32_bf16 v[26:29], v[234:237], v[158:161], v[26:29]
	v_mfma_f32_16x16x32_bf16 v[22:25], v[226:229], v[166:169], v[22:25]
	v_mfma_f32_16x16x32_bf16 v[18:21], v[234:237], v[166:169], v[18:21]
	v_mfma_f32_16x16x32_bf16 v[12:15], v[226:229], v[178:181], v[12:15]
	v_mfma_f32_16x16x32_bf16 v[8:11], v[234:237], v[178:181], v[8:11]
	v_mfma_f32_16x16x32_bf16 v[4:7], v[226:229], v[218:221], v[4:7]
	v_mfma_f32_16x16x32_bf16 v[0:3], v[234:237], v[218:221], v[0:3]
	v_mfma_f32_16x16x32_bf16 v[30:33], v[230:233], v[162:165], v[30:33]
	v_mfma_f32_16x16x32_bf16 v[26:29], v[238:241], v[162:165], v[26:29]
	v_mfma_f32_16x16x32_bf16 v[22:25], v[230:233], v[170:173], v[22:25]
	v_mfma_f32_16x16x32_bf16 v[18:21], v[238:241], v[170:173], v[18:21]
	v_mfma_f32_16x16x32_bf16 v[12:15], v[230:233], v[214:217], v[12:15]
	v_mfma_f32_16x16x32_bf16 v[8:11], v[238:241], v[214:217], v[8:11]
	v_mfma_f32_16x16x32_bf16 v[4:7], v[230:233], v[222:225], v[4:7]
	v_mfma_f32_16x16x32_bf16 v[0:3], v[238:241], v[222:225], v[0:3]
	s_add_i32 s67, s67, 2
	s_addk_i32 s68, 0x100
	s_cmp_lt_u32 s67, 28
	s_barrier
	s_cbranch_scc1 .LBB0_225
	v_mov_b32_e32 v150, v130
	s_or_b32 s8, s8, 0x80f80
	v_and_b32_e32 v158, 15, v150
	v_bfe_u32 v132, v150, 4, 2
	v_lshlrev_b32_e32 v134, 2, v150
	v_bfe_u32 v152, v150, 6, 2
	v_lshlrev_b32_e32 v151, 4, v132
	v_lshlrev_b32_e32 v133, 6, v158
	v_and_b32_e32 v139, 32, v134
	v_lshlrev_b32_e32 v138, 12, v152
	v_bitop3_b32 v153, v151, v139, v133 bitop3:0x36
	v_add3_u32 v133, s78, v153, v138
	ds_read_b128 v[134:137], v133
	ds_read_b128 v[154:157], v133 offset:1024
	ds_read_b128 v[160:163], v133 offset:2048
	ds_read_b128 v[164:167], v133 offset:3072
	v_ashrrev_i32_e32 v133, 2, v150
	v_lshlrev_b32_e32 v172, 6, v150
	v_and_b32_e32 v133, 0xffffffc0, v133
	v_and_b32_e32 v172, 0x3c0, v172
	v_lshlrev_b32_e32 v159, 7, v133
	v_bitop3_b32 v139, v172, v139, v151 bitop3:0x36
	s_waitcnt vmcnt(0)
	v_add3_u32 v176, 0, v153, v159
	v_add3_u32 v139, 0, v139, v159
	s_mov_b32 m0, s7
	ds_read_b128 v[168:171], v176
	ds_read_b128 v[178:181], v176 offset:1024
	ds_read_b128 v[214:217], v139 offset:2048
	ds_read_b128 v[218:221], v139 offset:3072
	ds_read_b128 v[222:225], v139 offset:4096
	ds_read_b128 v[226:229], v139 offset:5120
	ds_read_b128 v[230:233], v139 offset:6144
	ds_read_b128 v[234:237], v139 offset:7168
	buffer_load_dwordx4 v140, s[48:51], s8 offen lds
	s_mov_b32 m0, s6
	s_nop 0
	buffer_load_dwordx4 v141, s[48:51], s8 offen lds
	s_barrier
	s_waitcnt lgkmcnt(0)
	s_waitcnt lgkmcnt(0)
	v_mfma_f32_16x16x32_bf16 v[126:129], v[134:137], v[168:171], v[126:129]
	v_mfma_f32_16x16x32_bf16 v[122:125], v[160:163], v[168:171], v[122:125]
	v_mfma_f32_16x16x32_bf16 v[118:121], v[134:137], v[214:217], v[118:121]
	v_mfma_f32_16x16x32_bf16 v[114:117], v[160:163], v[214:217], v[114:117]
	v_mfma_f32_16x16x32_bf16 v[110:113], v[134:137], v[222:225], v[110:113]
	v_mfma_f32_16x16x32_bf16 v[106:109], v[160:163], v[222:225], v[106:109]
	v_mfma_f32_16x16x32_bf16 v[102:105], v[134:137], v[230:233], v[102:105]
	v_mfma_f32_16x16x32_bf16 v[98:101], v[160:163], v[230:233], v[98:101]
	v_mfma_f32_16x16x32_bf16 v[126:129], v[154:157], v[178:181], v[126:129]
	v_mfma_f32_16x16x32_bf16 v[122:125], v[164:167], v[178:181], v[122:125]
	v_mfma_f32_16x16x32_bf16 v[118:121], v[154:157], v[218:221], v[118:121]
	v_mfma_f32_16x16x32_bf16 v[114:117], v[164:167], v[218:221], v[114:117]
	v_mfma_f32_16x16x32_bf16 v[110:113], v[154:157], v[226:229], v[110:113]
	v_mfma_f32_16x16x32_bf16 v[106:109], v[164:167], v[226:229], v[106:109]
	v_mfma_f32_16x16x32_bf16 v[102:105], v[154:157], v[234:237], v[102:105]
	v_mfma_f32_16x16x32_bf16 v[98:101], v[164:167], v[234:237], v[98:101]
	v_add3_u32 v159, s77, v153, v138
	s_barrier
	ds_read_b128 v[238:241], v159
	ds_read_b128 v[242:245], v159 offset:1024
	ds_read_b128 v[246:249], v159 offset:2048
	ds_read_b128 v[250:253], v159 offset:3072
	s_barrier
	s_waitcnt lgkmcnt(0)
	s_waitcnt lgkmcnt(0)
	v_mfma_f32_16x16x32_bf16 v[94:97], v[238:241], v[168:171], v[94:97]
	v_mfma_f32_16x16x32_bf16 v[182:185], v[242:245], v[178:181], v[94:97]
	v_mfma_f32_16x16x32_bf16 v[90:93], v[246:249], v[168:171], v[90:93]
	v_mfma_f32_16x16x32_bf16 v[86:89], v[238:241], v[214:217], v[86:89]
	v_mfma_f32_16x16x32_bf16 v[82:85], v[246:249], v[214:217], v[82:85]
	v_mfma_f32_16x16x32_bf16 v[78:81], v[238:241], v[222:225], v[78:81]
	v_mfma_f32_16x16x32_bf16 v[74:77], v[246:249], v[222:225], v[74:77]
	v_mfma_f32_16x16x32_bf16 v[70:73], v[238:241], v[230:233], v[70:73]
	v_mfma_f32_16x16x32_bf16 v[66:69], v[246:249], v[230:233], v[66:69]
	v_mfma_f32_16x16x32_bf16 v[168:171], v[250:253], v[178:181], v[90:93]
	v_mfma_f32_16x16x32_bf16 v[178:181], v[242:245], v[218:221], v[86:89]
	v_mfma_f32_16x16x32_bf16 v[214:217], v[250:253], v[218:221], v[82:85]
	v_mfma_f32_16x16x32_bf16 v[218:221], v[242:245], v[226:229], v[78:81]
	v_mfma_f32_16x16x32_bf16 v[222:225], v[250:253], v[226:229], v[74:77]
	v_mfma_f32_16x16x32_bf16 v[226:229], v[242:245], v[234:237], v[70:73]
	v_mfma_f32_16x16x32_bf16 v[230:233], v[250:253], v[234:237], v[66:69]
	s_barrier
	s_nop 0
	ds_read_b128 v[66:69], v176 offset:16384
	ds_read_b128 v[70:73], v176 offset:17408
	ds_read_b128 v[74:77], v139 offset:18432
	ds_read_b128 v[78:81], v139 offset:19456
	ds_read_b128 v[82:85], v139 offset:20480
	ds_read_b128 v[86:89], v139 offset:21504
	ds_read_b128 v[90:93], v139 offset:22528
	ds_read_b128 v[94:97], v139 offset:23552
	s_waitcnt vmcnt(4)
	s_barrier
	s_waitcnt lgkmcnt(0)
	s_waitcnt lgkmcnt(0)
	v_mfma_f32_16x16x32_bf16 v[62:65], v[134:137], v[66:69], v[62:65]
	v_mfma_f32_16x16x32_bf16 v[58:61], v[160:163], v[66:69], v[58:61]
	v_mfma_f32_16x16x32_bf16 v[54:57], v[134:137], v[74:77], v[54:57]
	v_mfma_f32_16x16x32_bf16 v[50:53], v[160:163], v[74:77], v[50:53]
	v_mfma_f32_16x16x32_bf16 v[46:49], v[134:137], v[82:85], v[46:49]
	v_mfma_f32_16x16x32_bf16 v[42:45], v[160:163], v[82:85], v[42:45]
	v_mfma_f32_16x16x32_bf16 v[38:41], v[134:137], v[90:93], v[38:41]
	v_mfma_f32_16x16x32_bf16 v[34:37], v[160:163], v[90:93], v[34:37]
	v_mfma_f32_16x16x32_bf16 v[62:65], v[154:157], v[70:73], v[62:65]
	v_mfma_f32_16x16x32_bf16 v[58:61], v[164:167], v[70:73], v[58:61]
	v_mfma_f32_16x16x32_bf16 v[54:57], v[154:157], v[78:81], v[54:57]
	v_mfma_f32_16x16x32_bf16 v[50:53], v[164:167], v[78:81], v[50:53]
	v_mfma_f32_16x16x32_bf16 v[46:49], v[154:157], v[86:89], v[46:49]
	v_mfma_f32_16x16x32_bf16 v[42:45], v[164:167], v[86:89], v[42:45]
	v_mfma_f32_16x16x32_bf16 v[38:41], v[154:157], v[94:97], v[38:41]
	v_mfma_f32_16x16x32_bf16 v[34:37], v[164:167], v[94:97], v[34:37]
	v_mfma_f32_16x16x32_bf16 v[30:33], v[238:241], v[66:69], v[30:33]
	v_mfma_f32_16x16x32_bf16 v[26:29], v[246:249], v[66:69], v[26:29]
	v_mfma_f32_16x16x32_bf16 v[22:25], v[238:241], v[74:77], v[22:25]
	v_mfma_f32_16x16x32_bf16 v[18:21], v[246:249], v[74:77], v[18:21]
	v_mfma_f32_16x16x32_bf16 v[12:15], v[238:241], v[82:85], v[12:15]
	v_mfma_f32_16x16x32_bf16 v[8:11], v[246:249], v[82:85], v[8:11]
	v_mfma_f32_16x16x32_bf16 v[4:7], v[238:241], v[90:93], v[4:7]
	v_mfma_f32_16x16x32_bf16 v[0:3], v[246:249], v[90:93], v[0:3]
	v_mfma_f32_16x16x32_bf16 v[134:137], v[242:245], v[70:73], v[30:33]
	v_mfma_f32_16x16x32_bf16 v[154:157], v[250:253], v[70:73], v[26:29]
	v_mfma_f32_16x16x32_bf16 v[160:163], v[242:245], v[78:81], v[22:25]
	v_mfma_f32_16x16x32_bf16 v[164:167], v[250:253], v[78:81], v[18:21]
	v_mfma_f32_16x16x32_bf16 v[234:237], v[242:245], v[86:89], v[12:15]
	v_mfma_f32_16x16x32_bf16 v[82:85], v[250:253], v[86:89], v[8:11]
	v_mfma_f32_16x16x32_bf16 v[238:241], v[242:245], v[94:97], v[4:7]
	v_mfma_f32_16x16x32_bf16 v[242:245], v[250:253], v[94:97], v[0:3]
	s_nop 1
	v_add3_u32 v0, s2, v153, v138
	s_barrier
	ds_read_b128 v[246:249], v0
	ds_read_b128 v[250:253], v0 offset:1024
	ds_read_b128 v[200:203], v0 offset:2048
	ds_read_b128 v[172:175], v0 offset:3072
	ds_read_b128 v[4:7], v176 offset:32768
	ds_read_b128 v[8:11], v176 offset:33792
	ds_read_b128 v[12:15], v139 offset:34816
	ds_read_b128 v[18:21], v139 offset:35840
	ds_read_b128 v[22:25], v139 offset:36864
	ds_read_b128 v[26:29], v139 offset:37888
	ds_read_b128 v[30:33], v139 offset:38912
	ds_read_b128 v[208:211], v139 offset:39936
	s_waitcnt vmcnt(2)
	s_barrier
	s_waitcnt lgkmcnt(0)
	s_waitcnt lgkmcnt(0)
	v_mfma_f32_16x16x32_bf16 v[0:3], v[246:249], v[4:7], v[126:129]
	v_mfma_f32_16x16x32_bf16 v[126:129], v[250:253], v[8:11], v[0:3]
	v_mfma_f32_16x16x32_bf16 v[0:3], v[200:203], v[4:7], v[122:125]
	v_mfma_f32_16x16x32_bf16 v[122:125], v[172:175], v[8:11], v[0:3]
	v_mfma_f32_16x16x32_bf16 v[0:3], v[246:249], v[12:15], v[118:121]
	v_mfma_f32_16x16x32_bf16 v[90:93], v[250:253], v[18:21], v[0:3]
	v_mfma_f32_16x16x32_bf16 v[0:3], v[200:203], v[12:15], v[114:117]
	v_mfma_f32_16x16x32_bf16 v[94:97], v[172:175], v[18:21], v[0:3]
	v_mfma_f32_16x16x32_bf16 v[0:3], v[246:249], v[22:25], v[110:113]
	v_mfma_f32_16x16x32_bf16 v[74:77], v[250:253], v[26:29], v[0:3]
	v_mfma_f32_16x16x32_bf16 v[0:3], v[200:203], v[22:25], v[106:109]
	v_mfma_f32_16x16x32_bf16 v[86:89], v[172:175], v[26:29], v[0:3]
	v_mfma_f32_16x16x32_bf16 v[0:3], v[246:249], v[30:33], v[102:105]
	v_mfma_f32_16x16x32_bf16 v[196:199], v[250:253], v[208:211], v[0:3]
	v_mfma_f32_16x16x32_bf16 v[0:3], v[200:203], v[30:33], v[98:101]
	v_mfma_f32_16x16x32_bf16 v[78:81], v[172:175], v[208:211], v[0:3]
	v_add3_u32 v70, s91, v153, v138
	s_barrier
	ds_read_b128 v[204:207], v70
	s_nop 2
	ds_read_b128 v[0:3], v70 offset:1024
	ds_read_b128 v[66:69], v70 offset:2048
	ds_read_b128 v[70:73], v70 offset:3072
	s_waitcnt vmcnt(0)
	s_barrier
	s_waitcnt lgkmcnt(0)
	s_waitcnt lgkmcnt(0)
	v_mfma_f32_16x16x32_bf16 v[98:101], v[204:207], v[4:7], v[182:185]
	v_mfma_f32_16x16x32_bf16 v[4:7], v[66:69], v[4:7], v[168:171]
	v_mfma_f32_16x16x32_bf16 v[98:101], v[0:3], v[8:11], v[98:101]
	v_mfma_f32_16x16x32_bf16 v[102:105], v[70:73], v[8:11], v[4:7]
	v_mfma_f32_16x16x32_bf16 v[8:11], v[204:207], v[12:15], v[178:181]
	v_mfma_f32_16x16x32_bf16 v[12:15], v[66:69], v[12:15], v[214:217]
	v_mfma_f32_16x16x32_bf16 v[8:11], v[0:3], v[18:21], v[8:11]
	v_mfma_f32_16x16x32_bf16 v[12:15], v[70:73], v[18:21], v[12:15]
	v_mfma_f32_16x16x32_bf16 v[18:21], v[204:207], v[22:25], v[218:221]
	v_mfma_f32_16x16x32_bf16 v[22:25], v[66:69], v[22:25], v[222:225]
	v_mfma_f32_16x16x32_bf16 v[18:21], v[0:3], v[26:29], v[18:21]
	v_mfma_f32_16x16x32_bf16 v[22:25], v[70:73], v[26:29], v[22:25]
	v_mfma_f32_16x16x32_bf16 v[26:29], v[204:207], v[30:33], v[226:229]
	v_mfma_f32_16x16x32_bf16 v[30:33], v[66:69], v[30:33], v[230:233]
	v_mfma_f32_16x16x32_bf16 v[26:29], v[0:3], v[208:211], v[26:29]
	v_mfma_f32_16x16x32_bf16 v[30:33], v[70:73], v[208:211], v[30:33]
	s_barrier
	ds_read_b128 v[168:171], v176 offset:49152
	ds_read_b128 v[178:181], v176 offset:50176
	ds_read_b128 v[208:211], v139 offset:51200
	ds_read_b128 v[214:217], v139 offset:52224
	ds_read_b128 v[218:221], v139 offset:53248
	ds_read_b128 v[222:225], v139 offset:54272
	ds_read_b128 v[226:229], v139 offset:55296
	ds_read_b128 v[230:233], v139 offset:56320
	s_barrier
	s_waitcnt lgkmcnt(0)
	s_waitcnt lgkmcnt(0)
	v_mfma_f32_16x16x32_bf16 v[62:65], v[246:249], v[168:171], v[62:65]
	v_mfma_f32_16x16x32_bf16 v[58:61], v[200:203], v[168:171], v[58:61]
	v_mfma_f32_16x16x32_bf16 v[54:57], v[246:249], v[208:211], v[54:57]
	v_mfma_f32_16x16x32_bf16 v[50:53], v[200:203], v[208:211], v[50:53]
	v_mfma_f32_16x16x32_bf16 v[46:49], v[246:249], v[218:221], v[46:49]
	v_mfma_f32_16x16x32_bf16 v[42:45], v[200:203], v[218:221], v[42:45]
	v_mfma_f32_16x16x32_bf16 v[38:41], v[246:249], v[226:229], v[38:41]
	v_mfma_f32_16x16x32_bf16 v[34:37], v[200:203], v[226:229], v[34:37]
	v_mfma_f32_16x16x32_bf16 v[4:7], v[250:253], v[178:181], v[62:65]
	v_mfma_f32_16x16x32_bf16 v[182:185], v[172:175], v[178:181], v[58:61]
	v_mfma_f32_16x16x32_bf16 v[114:117], v[250:253], v[214:217], v[54:57]
	v_mfma_f32_16x16x32_bf16 v[118:121], v[172:175], v[214:217], v[50:53]
	v_mfma_f32_16x16x32_bf16 v[106:109], v[250:253], v[222:225], v[46:49]
	v_mfma_f32_16x16x32_bf16 v[110:113], v[172:175], v[222:225], v[42:45]
	v_mfma_f32_16x16x32_bf16 v[246:249], v[250:253], v[230:233], v[38:41]
	v_mfma_f32_16x16x32_bf16 v[250:253], v[172:175], v[230:233], v[34:37]
	v_mfma_f32_16x16x32_bf16 v[34:37], v[204:207], v[168:171], v[134:137]
	v_mfma_f32_16x16x32_bf16 v[42:45], v[204:207], v[208:211], v[160:163]
	v_mfma_f32_16x16x32_bf16 v[50:53], v[204:207], v[218:221], v[234:237]
	v_mfma_f32_16x16x32_bf16 v[58:61], v[204:207], v[226:229], v[238:241]
	v_mfma_f32_16x16x32_bf16 v[34:37], v[0:3], v[178:181], v[34:37]
	v_mfma_f32_16x16x32_bf16 v[38:41], v[66:69], v[168:171], v[154:157]
	v_mfma_f32_16x16x32_bf16 v[42:45], v[0:3], v[214:217], v[42:45]
	v_mfma_f32_16x16x32_bf16 v[46:49], v[66:69], v[208:211], v[164:167]
	v_mfma_f32_16x16x32_bf16 v[50:53], v[0:3], v[222:225], v[50:53]
	v_mfma_f32_16x16x32_bf16 v[54:57], v[66:69], v[218:221], v[82:85]
	v_mfma_f32_16x16x32_bf16 v[58:61], v[0:3], v[230:233], v[58:61]
	v_mfma_f32_16x16x32_bf16 v[0:3], v[66:69], v[226:229], v[242:245]
	v_mfma_f32_16x16x32_bf16 v[38:41], v[70:73], v[178:181], v[38:41]
	v_mfma_f32_16x16x32_bf16 v[46:49], v[70:73], v[214:217], v[46:49]
	v_mfma_f32_16x16x32_bf16 v[54:57], v[70:73], v[222:225], v[54:57]
	v_mfma_f32_16x16x32_bf16 v[62:65], v[70:73], v[230:233], v[0:3]
	s_movk_i32 s0, 0x100
	v_cmp_gt_u32_e32 vcc, s0, v150
	s_barrier
	s_and_saveexec_b64 s[6:7], vcc
	s_cbranch_execz .LBB0_228
	s_barrier

.LBB0_526:
	ds_read_b128 v[144:147], v136
	ds_read_b128 v[148:151], v136 offset:1024
	ds_read_b128 v[152:155], v136 offset:2048
	ds_read_b128 v[156:159], v136 offset:3072
	s_add_i32 s35, s15, s34
	s_add_i32 s36, s35, 0x80080
	s_mov_b32 m0, s7
	ds_read_b128 v[160:163], v137
	ds_read_b128 v[164:167], v137 offset:1024
	ds_read_b128 v[168:171], v138
	ds_read_b128 v[172:175], v138 offset:1024
	ds_read_b128 v[178:181], v139
	ds_read_b128 v[182:185], v139 offset:1024
	ds_read_b128 v[196:199], v140
	ds_read_b128 v[200:203], v140 offset:1024
	buffer_load_dwordx4 v134, s[48:51], s36 offen lds
	s_mov_b32 m0, s6
	s_nop 0
	buffer_load_dwordx4 v135, s[48:51], s36 offen lds
	s_waitcnt lgkmcnt(8)
	s_barrier
	s_waitcnt lgkmcnt(0)
	s_waitcnt lgkmcnt(7)
	v_mfma_f32_16x16x32_bf16 v[126:129], v[144:147], v[160:163], v[126:129]
	v_mfma_f32_16x16x32_bf16 v[122:125], v[152:155], v[160:163], v[122:125]
	s_waitcnt lgkmcnt(5)
	v_mfma_f32_16x16x32_bf16 v[118:121], v[144:147], v[168:171], v[118:121]
	v_mfma_f32_16x16x32_bf16 v[114:117], v[152:155], v[168:171], v[114:117]
	s_waitcnt lgkmcnt(3)
	v_mfma_f32_16x16x32_bf16 v[110:113], v[144:147], v[178:181], v[110:113]
	v_mfma_f32_16x16x32_bf16 v[106:109], v[152:155], v[178:181], v[106:109]
	s_waitcnt lgkmcnt(1)
	v_mfma_f32_16x16x32_bf16 v[102:105], v[144:147], v[196:199], v[102:105]
	v_mfma_f32_16x16x32_bf16 v[98:101], v[152:155], v[196:199], v[98:101]
	v_mfma_f32_16x16x32_bf16 v[126:129], v[148:151], v[164:167], v[126:129]
	v_mfma_f32_16x16x32_bf16 v[122:125], v[156:159], v[164:167], v[122:125]
	v_mfma_f32_16x16x32_bf16 v[118:121], v[148:151], v[172:175], v[118:121]
	v_mfma_f32_16x16x32_bf16 v[114:117], v[156:159], v[172:175], v[114:117]
	v_mfma_f32_16x16x32_bf16 v[110:113], v[148:151], v[182:185], v[110:113]
	v_mfma_f32_16x16x32_bf16 v[106:109], v[156:159], v[182:185], v[106:109]
	s_waitcnt lgkmcnt(0)
	v_mfma_f32_16x16x32_bf16 v[102:105], v[148:151], v[200:203], v[102:105]
	v_mfma_f32_16x16x32_bf16 v[98:101], v[156:159], v[200:203], v[98:101]
	s_barrier
	s_add_i32 s36, s16, s34
	s_add_i32 s37, s36, 0x100
	s_mov_b32 m0, s18
	ds_read_b128 v[204:207], v141
	ds_read_b128 v[208:211], v141 offset:1024
	ds_read_b128 v[214:217], v141 offset:2048
	ds_read_b128 v[218:221], v141 offset:3072
	buffer_load_dwordx4 v134, s[52:55], s37 offen lds
	s_mov_b32 m0, s19
	s_nop 0
	buffer_load_dwordx4 v135, s[52:55], s37 offen lds
	s_barrier
	s_waitcnt lgkmcnt(0)
	s_waitcnt lgkmcnt(3)
	v_mfma_f32_16x16x32_bf16 v[94:97], v[204:207], v[160:163], v[94:97]
	s_waitcnt lgkmcnt(1)
	v_mfma_f32_16x16x32_bf16 v[90:93], v[214:217], v[160:163], v[90:93]
	v_mfma_f32_16x16x32_bf16 v[86:89], v[204:207], v[168:171], v[86:89]
	v_mfma_f32_16x16x32_bf16 v[82:85], v[214:217], v[168:171], v[82:85]
	v_mfma_f32_16x16x32_bf16 v[78:81], v[204:207], v[178:181], v[78:81]
	v_mfma_f32_16x16x32_bf16 v[74:77], v[214:217], v[178:181], v[74:77]
	v_mfma_f32_16x16x32_bf16 v[70:73], v[204:207], v[196:199], v[70:73]
	v_mfma_f32_16x16x32_bf16 v[66:69], v[214:217], v[196:199], v[66:69]
	v_mfma_f32_16x16x32_bf16 v[94:97], v[208:211], v[164:167], v[94:97]
	s_waitcnt lgkmcnt(0)
	v_mfma_f32_16x16x32_bf16 v[90:93], v[218:221], v[164:167], v[90:93]
	v_mfma_f32_16x16x32_bf16 v[86:89], v[208:211], v[172:175], v[86:89]
	v_mfma_f32_16x16x32_bf16 v[82:85], v[218:221], v[172:175], v[82:85]
	v_mfma_f32_16x16x32_bf16 v[78:81], v[208:211], v[182:185], v[78:81]
	v_mfma_f32_16x16x32_bf16 v[74:77], v[218:221], v[182:185], v[74:77]
	v_mfma_f32_16x16x32_bf16 v[70:73], v[208:211], v[200:203], v[70:73]
	v_mfma_f32_16x16x32_bf16 v[66:69], v[218:221], v[200:203], v[66:69]
	s_add_i32 s37, s35, 0x100
	s_mov_b32 m0, s17
	s_barrier
	ds_read_b128 v[160:163], v137 offset:16384
	ds_read_b128 v[164:167], v137 offset:17408
	ds_read_b128 v[168:171], v138 offset:16384
	ds_read_b128 v[172:175], v138 offset:17408
	ds_read_b128 v[178:181], v139 offset:16384
	ds_read_b128 v[182:185], v139 offset:17408
	ds_read_b128 v[196:199], v140 offset:16384
	ds_read_b128 v[200:203], v140 offset:17408
	buffer_load_dwordx4 v134, s[48:51], s37 offen lds
	s_mov_b32 m0, s20
	s_nop 0
	buffer_load_dwordx4 v135, s[48:51], s37 offen lds
	s_barrier
	s_waitcnt lgkmcnt(0)
	s_waitcnt lgkmcnt(7)
	v_mfma_f32_16x16x32_bf16 v[62:65], v[144:147], v[160:163], v[62:65]
	v_mfma_f32_16x16x32_bf16 v[58:61], v[152:155], v[160:163], v[58:61]
	s_waitcnt lgkmcnt(5)
	v_mfma_f32_16x16x32_bf16 v[54:57], v[144:147], v[168:171], v[54:57]
	v_mfma_f32_16x16x32_bf16 v[50:53], v[152:155], v[168:171], v[50:53]
	s_waitcnt lgkmcnt(3)
	v_mfma_f32_16x16x32_bf16 v[46:49], v[144:147], v[178:181], v[46:49]
	v_mfma_f32_16x16x32_bf16 v[42:45], v[152:155], v[178:181], v[42:45]
	s_waitcnt lgkmcnt(1)
	v_mfma_f32_16x16x32_bf16 v[38:41], v[144:147], v[196:199], v[38:41]
	v_mfma_f32_16x16x32_bf16 v[34:37], v[152:155], v[196:199], v[34:37]
	v_mfma_f32_16x16x32_bf16 v[62:65], v[148:151], v[164:167], v[62:65]
	v_mfma_f32_16x16x32_bf16 v[58:61], v[156:159], v[164:167], v[58:61]
	v_mfma_f32_16x16x32_bf16 v[54:57], v[148:151], v[172:175], v[54:57]
	v_mfma_f32_16x16x32_bf16 v[50:53], v[156:159], v[172:175], v[50:53]
	v_mfma_f32_16x16x32_bf16 v[46:49], v[148:151], v[182:185], v[46:49]
	v_mfma_f32_16x16x32_bf16 v[42:45], v[156:159], v[182:185], v[42:45]
	s_waitcnt lgkmcnt(0)
	v_mfma_f32_16x16x32_bf16 v[38:41], v[148:151], v[200:203], v[38:41]
	v_mfma_f32_16x16x32_bf16 v[34:37], v[156:159], v[200:203], v[34:37]
	s_barrier
	s_add_i32 s37, s36, 0x80100
	s_mov_b32 m0, s21
	s_nop 0
	buffer_load_dwordx4 v134, s[52:55], s37 offen lds
	s_mov_b32 m0, s22
	s_nop 0
	buffer_load_dwordx4 v135, s[52:55], s37 offen lds
	s_waitcnt vmcnt(6)
	s_barrier
	v_mfma_f32_16x16x32_bf16 v[30:33], v[204:207], v[160:163], v[30:33]
	v_mfma_f32_16x16x32_bf16 v[26:29], v[214:217], v[160:163], v[26:29]
	v_mfma_f32_16x16x32_bf16 v[22:25], v[204:207], v[168:171], v[22:25]
	v_mfma_f32_16x16x32_bf16 v[18:21], v[214:217], v[168:171], v[18:21]
	v_mfma_f32_16x16x32_bf16 v[12:15], v[204:207], v[178:181], v[12:15]
	v_mfma_f32_16x16x32_bf16 v[8:11], v[214:217], v[178:181], v[8:11]
	v_mfma_f32_16x16x32_bf16 v[4:7], v[204:207], v[196:199], v[4:7]
	v_mfma_f32_16x16x32_bf16 v[0:3], v[214:217], v[196:199], v[0:3]
	v_mfma_f32_16x16x32_bf16 v[30:33], v[208:211], v[164:167], v[30:33]
	v_mfma_f32_16x16x32_bf16 v[26:29], v[218:221], v[164:167], v[26:29]
	v_mfma_f32_16x16x32_bf16 v[22:25], v[208:211], v[172:175], v[22:25]
	v_mfma_f32_16x16x32_bf16 v[18:21], v[218:221], v[172:175], v[18:21]
	v_mfma_f32_16x16x32_bf16 v[12:15], v[208:211], v[182:185], v[12:15]
	v_mfma_f32_16x16x32_bf16 v[8:11], v[218:221], v[182:185], v[8:11]
	v_mfma_f32_16x16x32_bf16 v[4:7], v[208:211], v[200:203], v[4:7]
	v_mfma_f32_16x16x32_bf16 v[0:3], v[218:221], v[200:203], v[0:3]
	s_barrier
	ds_read_b128 v[144:147], v142
	ds_read_b128 v[148:151], v142 offset:1024
	ds_read_b128 v[152:155], v142 offset:2048
	ds_read_b128 v[156:159], v142 offset:3072
	s_add_i32 s37, s35, 0x80100
	s_mov_b32 m0, s23
	ds_read_b128 v[160:163], v137 offset:32768
	ds_read_b128 v[164:167], v137 offset:33792
	ds_read_b128 v[168:171], v138 offset:32768
	ds_read_b128 v[172:175], v138 offset:33792
	ds_read_b128 v[178:181], v139 offset:32768
	ds_read_b128 v[182:185], v139 offset:33792
	ds_read_b128 v[196:199], v140 offset:32768
	ds_read_b128 v[200:203], v140 offset:33792
	buffer_load_dwordx4 v134, s[48:51], s37 offen lds
	s_mov_b32 m0, s24
	s_nop 0
	buffer_load_dwordx4 v135, s[48:51], s37 offen lds
	s_waitcnt lgkmcnt(8)
	s_barrier
	s_waitcnt lgkmcnt(0)
	s_waitcnt lgkmcnt(7)
	v_mfma_f32_16x16x32_bf16 v[126:129], v[144:147], v[160:163], v[126:129]
	v_mfma_f32_16x16x32_bf16 v[122:125], v[152:155], v[160:163], v[122:125]
	s_waitcnt lgkmcnt(5)
	v_mfma_f32_16x16x32_bf16 v[118:121], v[144:147], v[168:171], v[118:121]
	v_mfma_f32_16x16x32_bf16 v[114:117], v[152:155], v[168:171], v[114:117]
	s_waitcnt lgkmcnt(3)
	v_mfma_f32_16x16x32_bf16 v[110:113], v[144:147], v[178:181], v[110:113]
	v_mfma_f32_16x16x32_bf16 v[106:109], v[152:155], v[178:181], v[106:109]
	s_waitcnt lgkmcnt(1)
	v_mfma_f32_16x16x32_bf16 v[102:105], v[144:147], v[196:199], v[102:105]
	v_mfma_f32_16x16x32_bf16 v[98:101], v[152:155], v[196:199], v[98:101]
	v_mfma_f32_16x16x32_bf16 v[126:129], v[148:151], v[164:167], v[126:129]
	v_mfma_f32_16x16x32_bf16 v[122:125], v[156:159], v[164:167], v[122:125]
	v_mfma_f32_16x16x32_bf16 v[118:121], v[148:151], v[172:175], v[118:121]
	v_mfma_f32_16x16x32_bf16 v[114:117], v[156:159], v[172:175], v[114:117]
	v_mfma_f32_16x16x32_bf16 v[110:113], v[148:151], v[182:185], v[110:113]
	v_mfma_f32_16x16x32_bf16 v[106:109], v[156:159], v[182:185], v[106:109]
	s_waitcnt lgkmcnt(0)
	v_mfma_f32_16x16x32_bf16 v[102:105], v[148:151], v[200:203], v[102:105]
	v_mfma_f32_16x16x32_bf16 v[98:101], v[156:159], v[200:203], v[98:101]
	s_barrier
	s_add_i32 s37, s36, 0x180
	s_mov_b32 m0, s25
	ds_read_b128 v[204:207], v143
	ds_read_b128 v[208:211], v143 offset:1024
	ds_read_b128 v[214:217], v143 offset:2048
	ds_read_b128 v[218:221], v143 offset:3072
	buffer_load_dwordx4 v134, s[52:55], s37 offen lds
	s_mov_b32 m0, s26
	s_nop 0
	buffer_load_dwordx4 v135, s[52:55], s37 offen lds
	s_barrier
	s_waitcnt lgkmcnt(0)
	s_waitcnt lgkmcnt(3)
	v_mfma_f32_16x16x32_bf16 v[94:97], v[204:207], v[160:163], v[94:97]
	s_waitcnt lgkmcnt(1)
	v_mfma_f32_16x16x32_bf16 v[90:93], v[214:217], v[160:163], v[90:93]
	v_mfma_f32_16x16x32_bf16 v[86:89], v[204:207], v[168:171], v[86:89]
	v_mfma_f32_16x16x32_bf16 v[82:85], v[214:217], v[168:171], v[82:85]
	v_mfma_f32_16x16x32_bf16 v[78:81], v[204:207], v[178:181], v[78:81]
	v_mfma_f32_16x16x32_bf16 v[74:77], v[214:217], v[178:181], v[74:77]
	v_mfma_f32_16x16x32_bf16 v[70:73], v[204:207], v[196:199], v[70:73]
	v_mfma_f32_16x16x32_bf16 v[66:69], v[214:217], v[196:199], v[66:69]
	v_mfma_f32_16x16x32_bf16 v[94:97], v[208:211], v[164:167], v[94:97]
	s_waitcnt lgkmcnt(0)
	v_mfma_f32_16x16x32_bf16 v[90:93], v[218:221], v[164:167], v[90:93]
	v_mfma_f32_16x16x32_bf16 v[86:89], v[208:211], v[172:175], v[86:89]
	v_mfma_f32_16x16x32_bf16 v[82:85], v[218:221], v[172:175], v[82:85]
	v_mfma_f32_16x16x32_bf16 v[78:81], v[208:211], v[182:185], v[78:81]
	v_mfma_f32_16x16x32_bf16 v[74:77], v[218:221], v[182:185], v[74:77]
	v_mfma_f32_16x16x32_bf16 v[70:73], v[208:211], v[200:203], v[70:73]
	v_mfma_f32_16x16x32_bf16 v[66:69], v[218:221], v[200:203], v[66:69]
	s_addk_i32 s35, 0x180
	s_mov_b32 m0, s27
	s_barrier
	ds_read_b128 v[160:163], v137 offset:49152
	ds_read_b128 v[164:167], v137 offset:50176
	ds_read_b128 v[168:171], v138 offset:49152
	ds_read_b128 v[172:175], v138 offset:50176
	ds_read_b128 v[178:181], v139 offset:49152
	ds_read_b128 v[182:185], v139 offset:50176
	ds_read_b128 v[196:199], v140 offset:49152
	ds_read_b128 v[200:203], v140 offset:50176
	buffer_load_dwordx4 v134, s[48:51], s35 offen lds
	s_mov_b32 m0, s28
	s_nop 0
	buffer_load_dwordx4 v135, s[48:51], s35 offen lds
	s_barrier
	s_waitcnt lgkmcnt(0)
	s_waitcnt lgkmcnt(7)
	v_mfma_f32_16x16x32_bf16 v[62:65], v[144:147], v[160:163], v[62:65]
	v_mfma_f32_16x16x32_bf16 v[58:61], v[152:155], v[160:163], v[58:61]
	s_waitcnt lgkmcnt(5)
	v_mfma_f32_16x16x32_bf16 v[54:57], v[144:147], v[168:171], v[54:57]
	v_mfma_f32_16x16x32_bf16 v[50:53], v[152:155], v[168:171], v[50:53]
	s_waitcnt lgkmcnt(3)
	v_mfma_f32_16x16x32_bf16 v[46:49], v[144:147], v[178:181], v[46:49]
	v_mfma_f32_16x16x32_bf16 v[42:45], v[152:155], v[178:181], v[42:45]
	s_waitcnt lgkmcnt(1)
	v_mfma_f32_16x16x32_bf16 v[38:41], v[144:147], v[196:199], v[38:41]
	v_mfma_f32_16x16x32_bf16 v[34:37], v[152:155], v[196:199], v[34:37]
	v_mfma_f32_16x16x32_bf16 v[62:65], v[148:151], v[164:167], v[62:65]
	v_mfma_f32_16x16x32_bf16 v[58:61], v[156:159], v[164:167], v[58:61]
	v_mfma_f32_16x16x32_bf16 v[54:57], v[148:151], v[172:175], v[54:57]
	v_mfma_f32_16x16x32_bf16 v[50:53], v[156:159], v[172:175], v[50:53]
	v_mfma_f32_16x16x32_bf16 v[46:49], v[148:151], v[182:185], v[46:49]
	v_mfma_f32_16x16x32_bf16 v[42:45], v[156:159], v[182:185], v[42:45]
	s_waitcnt lgkmcnt(0)
	v_mfma_f32_16x16x32_bf16 v[38:41], v[148:151], v[200:203], v[38:41]
	v_mfma_f32_16x16x32_bf16 v[34:37], v[156:159], v[200:203], v[34:37]
	s_barrier
	s_add_i32 s36, s36, 0x80180
	s_mov_b32 m0, s29
	s_nop 0
	buffer_load_dwordx4 v134, s[52:55], s36 offen lds
	s_mov_b32 m0, s30
	s_nop 0
	buffer_load_dwordx4 v135, s[52:55], s36 offen lds
	s_waitcnt vmcnt(6)
	s_barrier
	v_mfma_f32_16x16x32_bf16 v[30:33], v[204:207], v[160:163], v[30:33]
	v_mfma_f32_16x16x32_bf16 v[26:29], v[214:217], v[160:163], v[26:29]
	v_mfma_f32_16x16x32_bf16 v[22:25], v[204:207], v[168:171], v[22:25]
	v_mfma_f32_16x16x32_bf16 v[18:21], v[214:217], v[168:171], v[18:21]
	v_mfma_f32_16x16x32_bf16 v[12:15], v[204:207], v[178:181], v[12:15]
	v_mfma_f32_16x16x32_bf16 v[8:11], v[214:217], v[178:181], v[8:11]
	v_mfma_f32_16x16x32_bf16 v[4:7], v[204:207], v[196:199], v[4:7]
	v_mfma_f32_16x16x32_bf16 v[0:3], v[214:217], v[196:199], v[0:3]
	v_mfma_f32_16x16x32_bf16 v[30:33], v[208:211], v[164:167], v[30:33]
	v_mfma_f32_16x16x32_bf16 v[26:29], v[218:221], v[164:167], v[26:29]
	v_mfma_f32_16x16x32_bf16 v[22:25], v[208:211], v[172:175], v[22:25]
	v_mfma_f32_16x16x32_bf16 v[18:21], v[218:221], v[172:175], v[18:21]
	v_mfma_f32_16x16x32_bf16 v[12:15], v[208:211], v[182:185], v[12:15]
	v_mfma_f32_16x16x32_bf16 v[8:11], v[218:221], v[182:185], v[8:11]
	v_mfma_f32_16x16x32_bf16 v[4:7], v[208:211], v[200:203], v[4:7]
	v_mfma_f32_16x16x32_bf16 v[0:3], v[218:221], v[200:203], v[0:3]
	s_add_i32 s31, s31, 2
	s_addk_i32 s34, 0x100
	s_cmp_lt_u32 s31, 28
	s_barrier
	s_cbranch_scc1 .LBB0_526
	v_mov_b32_e32 v144, v130
	s_or_b32 s15, s15, 0x80f80
	v_and_b32_e32 v147, 15, v144
	v_bfe_u32 v146, v144, 4, 2
	v_lshlrev_b32_e32 v150, 2, v144
	v_bfe_u32 v145, v144, 6, 2
	v_lshlrev_b32_e32 v174, 4, v146
	v_lshlrev_b32_e32 v148, 6, v147
	v_and_b32_e32 v175, 32, v150
	v_lshlrev_b32_e32 v149, 12, v145
	v_bitop3_b32 v176, v174, v175, v148 bitop3:0x36
	v_add3_u32 v148, s78, v176, v149
	ds_read_b128 v[150:153], v148
	ds_read_b128 v[154:157], v148 offset:1024
	ds_read_b128 v[158:161], v148 offset:2048
	ds_read_b128 v[162:165], v148 offset:3072
	v_ashrrev_i32_e32 v148, 2, v144
	v_lshlrev_b32_e32 v178, 6, v144
	v_and_b32_e32 v148, 0xffffffc0, v148
	v_and_b32_e32 v178, 0x3c0, v178
	v_lshlrev_b32_e32 v177, 7, v148
	v_bitop3_b32 v174, v178, v175, v174 bitop3:0x36
	s_waitcnt vmcnt(0)
	v_add3_u32 v190, 0, v176, v177
	v_add3_u32 v174, 0, v174, v177
	s_mov_b32 m0, s7
	ds_read_b128 v[166:169], v190
	ds_read_b128 v[170:173], v190 offset:1024
	ds_read_b128 v[178:181], v174 offset:2048
	ds_read_b128 v[182:185], v174 offset:3072
	ds_read_b128 v[196:199], v174 offset:4096
	ds_read_b128 v[200:203], v174 offset:5120
	ds_read_b128 v[204:207], v174 offset:6144
	ds_read_b128 v[208:211], v174 offset:7168
	buffer_load_dwordx4 v134, s[48:51], s15 offen lds
	s_mov_b32 m0, s6
	s_nop 0
	buffer_load_dwordx4 v135, s[48:51], s15 offen lds
	s_barrier
	s_waitcnt lgkmcnt(0)
	s_waitcnt lgkmcnt(7)
	v_mfma_f32_16x16x32_bf16 v[126:129], v[150:153], v[166:169], v[126:129]
	v_mfma_f32_16x16x32_bf16 v[122:125], v[158:161], v[166:169], v[122:125]
	s_waitcnt lgkmcnt(5)
	v_mfma_f32_16x16x32_bf16 v[118:121], v[150:153], v[178:181], v[118:121]
	v_mfma_f32_16x16x32_bf16 v[114:117], v[158:161], v[178:181], v[114:117]
	s_waitcnt lgkmcnt(1)
	v_mfma_f32_16x16x32_bf16 v[102:105], v[150:153], v[204:207], v[102:105]
	v_mfma_f32_16x16x32_bf16 v[98:101], v[158:161], v[204:207], v[98:101]
	v_mfma_f32_16x16x32_bf16 v[126:129], v[154:157], v[170:173], v[126:129]
	v_mfma_f32_16x16x32_bf16 v[122:125], v[162:165], v[170:173], v[122:125]
	v_mfma_f32_16x16x32_bf16 v[118:121], v[154:157], v[182:185], v[118:121]
	v_mfma_f32_16x16x32_bf16 v[114:117], v[162:165], v[182:185], v[114:117]
	v_mfma_f32_16x16x32_bf16 v[110:113], v[150:153], v[196:199], v[110:113]
	v_mfma_f32_16x16x32_bf16 v[106:109], v[158:161], v[196:199], v[106:109]
	s_waitcnt lgkmcnt(0)
	v_mfma_f32_16x16x32_bf16 v[102:105], v[154:157], v[208:211], v[102:105]
	v_mfma_f32_16x16x32_bf16 v[98:101], v[162:165], v[208:211], v[98:101]
	v_mfma_f32_16x16x32_bf16 v[214:217], v[154:157], v[200:203], v[110:113]
	v_mfma_f32_16x16x32_bf16 v[218:221], v[162:165], v[200:203], v[106:109]
	v_add3_u32 v175, s77, v176, v149
	s_barrier
	ds_read_b128 v[106:109], v175
	ds_read_b128 v[110:113], v175 offset:1024
	ds_read_b128 v[222:225], v175 offset:2048
	ds_read_b128 v[226:229], v175 offset:3072
	s_barrier
	s_waitcnt lgkmcnt(0)
	s_waitcnt lgkmcnt(3)
	v_mfma_f32_16x16x32_bf16 v[94:97], v[106:109], v[166:169], v[94:97]
	s_waitcnt lgkmcnt(1)
	v_mfma_f32_16x16x32_bf16 v[82:85], v[222:225], v[178:181], v[82:85]
	v_mfma_f32_16x16x32_bf16 v[78:81], v[106:109], v[196:199], v[78:81]
	v_mfma_f32_16x16x32_bf16 v[74:77], v[222:225], v[196:199], v[74:77]
	v_mfma_f32_16x16x32_bf16 v[70:73], v[106:109], v[204:207], v[70:73]
	v_mfma_f32_16x16x32_bf16 v[66:69], v[222:225], v[204:207], v[66:69]
	v_mfma_f32_16x16x32_bf16 v[94:97], v[110:113], v[170:173], v[94:97]
	v_mfma_f32_16x16x32_bf16 v[90:93], v[222:225], v[166:169], v[90:93]
	v_mfma_f32_16x16x32_bf16 v[86:89], v[106:109], v[178:181], v[86:89]
	s_waitcnt lgkmcnt(0)
	v_mfma_f32_16x16x32_bf16 v[82:85], v[226:229], v[182:185], v[82:85]
	v_mfma_f32_16x16x32_bf16 v[78:81], v[110:113], v[200:203], v[78:81]
	v_mfma_f32_16x16x32_bf16 v[74:77], v[226:229], v[200:203], v[74:77]
	v_mfma_f32_16x16x32_bf16 v[70:73], v[110:113], v[208:211], v[70:73]
	v_mfma_f32_16x16x32_bf16 v[66:69], v[226:229], v[208:211], v[66:69]
	v_mfma_f32_16x16x32_bf16 v[166:169], v[226:229], v[170:173], v[90:93]
	v_mfma_f32_16x16x32_bf16 v[170:173], v[110:113], v[182:185], v[86:89]
	s_barrier
	s_nop 0
	ds_read_b128 v[86:89], v190 offset:16384
	ds_read_b128 v[90:93], v190 offset:17408
	ds_read_b128 v[178:181], v174 offset:18432
	ds_read_b128 v[182:185], v174 offset:19456
	ds_read_b128 v[196:199], v174 offset:20480
	ds_read_b128 v[200:203], v174 offset:21504
	ds_read_b128 v[204:207], v174 offset:22528
	ds_read_b128 v[208:211], v174 offset:23552
	s_waitcnt vmcnt(4)
	s_barrier
	s_waitcnt lgkmcnt(0)
	s_waitcnt lgkmcnt(5)
	v_mfma_f32_16x16x32_bf16 v[54:57], v[150:153], v[178:181], v[54:57]
	v_mfma_f32_16x16x32_bf16 v[50:53], v[158:161], v[178:181], v[50:53]
	v_mfma_f32_16x16x32_bf16 v[62:65], v[150:153], v[86:89], v[62:65]
	v_mfma_f32_16x16x32_bf16 v[58:61], v[158:161], v[86:89], v[58:61]
	s_waitcnt lgkmcnt(4)
	v_mfma_f32_16x16x32_bf16 v[54:57], v[154:157], v[182:185], v[54:57]
	v_mfma_f32_16x16x32_bf16 v[50:53], v[162:165], v[182:185], v[50:53]
	s_waitcnt lgkmcnt(3)
	v_mfma_f32_16x16x32_bf16 v[46:49], v[150:153], v[196:199], v[46:49]
	v_mfma_f32_16x16x32_bf16 v[42:45], v[158:161], v[196:199], v[42:45]
	s_waitcnt lgkmcnt(1)
	v_mfma_f32_16x16x32_bf16 v[38:41], v[150:153], v[204:207], v[38:41]
	v_mfma_f32_16x16x32_bf16 v[34:37], v[158:161], v[204:207], v[34:37]
	v_mfma_f32_16x16x32_bf16 v[230:233], v[154:157], v[90:93], v[62:65]
	v_mfma_f32_16x16x32_bf16 v[234:237], v[162:165], v[90:93], v[58:61]
	v_mfma_f32_16x16x32_bf16 v[238:241], v[154:157], v[200:203], v[46:49]
	v_mfma_f32_16x16x32_bf16 v[242:245], v[162:165], v[200:203], v[42:45]
	s_waitcnt lgkmcnt(0)
	v_mfma_f32_16x16x32_bf16 v[150:153], v[154:157], v[208:211], v[38:41]
	v_mfma_f32_16x16x32_bf16 v[154:157], v[162:165], v[208:211], v[34:37]
	v_mfma_f32_16x16x32_bf16 v[30:33], v[106:109], v[86:89], v[30:33]
	v_mfma_f32_16x16x32_bf16 v[26:29], v[222:225], v[86:89], v[26:29]
	v_mfma_f32_16x16x32_bf16 v[12:15], v[106:109], v[196:199], v[12:15]
	v_mfma_f32_16x16x32_bf16 v[8:11], v[222:225], v[196:199], v[8:11]
	v_mfma_f32_16x16x32_bf16 v[30:33], v[110:113], v[90:93], v[30:33]
	v_mfma_f32_16x16x32_bf16 v[26:29], v[226:229], v[90:93], v[26:29]
	v_mfma_f32_16x16x32_bf16 v[22:25], v[106:109], v[178:181], v[22:25]
	v_mfma_f32_16x16x32_bf16 v[18:21], v[222:225], v[178:181], v[18:21]
	v_mfma_f32_16x16x32_bf16 v[12:15], v[110:113], v[200:203], v[12:15]
	v_mfma_f32_16x16x32_bf16 v[8:11], v[226:229], v[200:203], v[8:11]
	v_mfma_f32_16x16x32_bf16 v[4:7], v[106:109], v[204:207], v[4:7]
	v_mfma_f32_16x16x32_bf16 v[0:3], v[222:225], v[204:207], v[0:3]
	v_mfma_f32_16x16x32_bf16 v[158:161], v[110:113], v[182:185], v[22:25]
	v_mfma_f32_16x16x32_bf16 v[162:165], v[226:229], v[182:185], v[18:21]
	v_mfma_f32_16x16x32_bf16 v[178:181], v[110:113], v[208:211], v[4:7]
	v_mfma_f32_16x16x32_bf16 v[182:185], v[226:229], v[208:211], v[0:3]
	v_add3_u32 v18, s2, v176, v149
	s_barrier
	s_nop 0
	ds_read_b128 v[0:3], v18
	ds_read_b128 v[4:7], v18 offset:1024
	ds_read_b128 v[196:199], v18 offset:2048
	ds_read_b128 v[200:203], v18 offset:3072
	ds_read_b128 v[18:21], v190 offset:32768
	ds_read_b128 v[22:25], v190 offset:33792
	ds_read_b128 v[42:45], v174 offset:34816
	ds_read_b128 v[46:49], v174 offset:35840
	ds_read_b128 v[204:207], v174 offset:36864
	ds_read_b128 v[208:211], v174 offset:37888
	ds_read_b128 v[222:225], v174 offset:38912
	ds_read_b128 v[226:229], v174 offset:39936
	s_waitcnt vmcnt(2)
	s_barrier
	s_waitcnt lgkmcnt(0)
	s_waitcnt lgkmcnt(7)
	v_mfma_f32_16x16x32_bf16 v[34:37], v[0:3], v[18:21], v[126:129]
	s_waitcnt lgkmcnt(6)
	v_mfma_f32_16x16x32_bf16 v[110:113], v[4:7], v[22:25], v[34:37]
	v_mfma_f32_16x16x32_bf16 v[34:37], v[196:199], v[18:21], v[122:125]
	v_mfma_f32_16x16x32_bf16 v[106:109], v[200:203], v[22:25], v[34:37]
	s_waitcnt lgkmcnt(5)
	v_mfma_f32_16x16x32_bf16 v[34:37], v[0:3], v[42:45], v[118:121]
	s_waitcnt lgkmcnt(4)
	v_mfma_f32_16x16x32_bf16 v[90:93], v[4:7], v[46:49], v[34:37]
	v_mfma_f32_16x16x32_bf16 v[34:37], v[196:199], v[42:45], v[114:117]
	v_mfma_f32_16x16x32_bf16 v[86:89], v[200:203], v[46:49], v[34:37]
	s_waitcnt lgkmcnt(3)
	v_mfma_f32_16x16x32_bf16 v[34:37], v[0:3], v[204:207], v[214:217]
	s_waitcnt lgkmcnt(2)
	v_mfma_f32_16x16x32_bf16 v[62:65], v[4:7], v[208:211], v[34:37]
	v_mfma_f32_16x16x32_bf16 v[34:37], v[196:199], v[204:207], v[218:221]
	v_mfma_f32_16x16x32_bf16 v[58:61], v[200:203], v[208:211], v[34:37]
	s_waitcnt lgkmcnt(1)
	v_mfma_f32_16x16x32_bf16 v[34:37], v[0:3], v[222:225], v[102:105]
	s_waitcnt lgkmcnt(0)
	v_mfma_f32_16x16x32_bf16 v[38:41], v[4:7], v[226:229], v[34:37]
	v_mfma_f32_16x16x32_bf16 v[34:37], v[196:199], v[222:225], v[98:101]
	v_mfma_f32_16x16x32_bf16 v[34:37], v[200:203], v[226:229], v[34:37]
	s_nop 0
	v_add3_u32 v98, s91, v176, v149
	s_barrier
	ds_read_b128 v[214:217], v98
	ds_read_b128 v[218:221], v98 offset:1024
	ds_read_b128 v[246:249], v98 offset:2048
	ds_read_b128 v[250:253], v98 offset:3072
	s_waitcnt vmcnt(0)
	s_barrier
	s_waitcnt lgkmcnt(0)
	s_waitcnt lgkmcnt(3)
	v_mfma_f32_16x16x32_bf16 v[94:97], v[214:217], v[18:21], v[94:97]
	s_waitcnt lgkmcnt(1)
	v_mfma_f32_16x16x32_bf16 v[18:21], v[246:249], v[18:21], v[166:169]
	s_waitcnt lgkmcnt(0)
	v_mfma_f32_16x16x32_bf16 v[122:125], v[250:253], v[22:25], v[18:21]
	v_mfma_f32_16x16x32_bf16 v[18:21], v[214:217], v[42:45], v[170:173]
	v_mfma_f32_16x16x32_bf16 v[118:121], v[218:221], v[46:49], v[18:21]
	v_mfma_f32_16x16x32_bf16 v[18:21], v[246:249], v[42:45], v[82:85]
	v_mfma_f32_16x16x32_bf16 v[114:117], v[250:253], v[46:49], v[18:21]
	v_mfma_f32_16x16x32_bf16 v[18:21], v[214:217], v[204:207], v[78:81]
	v_mfma_f32_16x16x32_bf16 v[102:105], v[218:221], v[208:211], v[18:21]
	v_mfma_f32_16x16x32_bf16 v[18:21], v[246:249], v[204:207], v[74:77]
	v_mfma_f32_16x16x32_bf16 v[126:129], v[218:221], v[22:25], v[94:97]
	v_mfma_f32_16x16x32_bf16 v[94:97], v[250:253], v[208:211], v[18:21]
	v_mfma_f32_16x16x32_bf16 v[18:21], v[214:217], v[222:225], v[70:73]
	v_mfma_f32_16x16x32_bf16 v[70:73], v[218:221], v[226:229], v[18:21]
	v_mfma_f32_16x16x32_bf16 v[18:21], v[246:249], v[222:225], v[66:69]
	v_mfma_f32_16x16x32_bf16 v[66:69], v[250:253], v[226:229], v[18:21]
	s_barrier
	ds_read_b128 v[82:85], v190 offset:49152
	ds_read_b128 v[166:169], v190 offset:50176
	ds_read_b128 v[170:173], v174 offset:51200
	ds_read_b128 v[204:207], v174 offset:52224
	ds_read_b128 v[208:211], v174 offset:53248
	ds_read_b128 v[222:225], v174 offset:54272
	ds_read_b128 v[226:229], v174 offset:55296
	ds_read_b128 v[174:177], v174 offset:56320
	s_barrier
	s_waitcnt lgkmcnt(0)
	s_waitcnt lgkmcnt(7)
	v_mfma_f32_16x16x32_bf16 v[18:21], v[0:3], v[82:85], v[230:233]
	s_waitcnt lgkmcnt(6)
	v_mfma_f32_16x16x32_bf16 v[78:81], v[4:7], v[166:169], v[18:21]
	v_mfma_f32_16x16x32_bf16 v[18:21], v[196:199], v[82:85], v[234:237]
	v_mfma_f32_16x16x32_bf16 v[74:77], v[200:203], v[166:169], v[18:21]
	s_waitcnt lgkmcnt(5)
	v_mfma_f32_16x16x32_bf16 v[18:21], v[0:3], v[170:173], v[54:57]
	s_waitcnt lgkmcnt(4)
	v_mfma_f32_16x16x32_bf16 v[46:49], v[4:7], v[204:207], v[18:21]
	v_mfma_f32_16x16x32_bf16 v[18:21], v[196:199], v[170:173], v[50:53]
	v_mfma_f32_16x16x32_bf16 v[42:45], v[200:203], v[204:207], v[18:21]
	s_waitcnt lgkmcnt(3)
	v_mfma_f32_16x16x32_bf16 v[18:21], v[0:3], v[208:211], v[238:241]
	s_waitcnt lgkmcnt(1)
	v_mfma_f32_16x16x32_bf16 v[0:3], v[0:3], v[226:229], v[150:153]
	v_mfma_f32_16x16x32_bf16 v[22:25], v[4:7], v[222:225], v[18:21]
	v_mfma_f32_16x16x32_bf16 v[18:21], v[196:199], v[208:211], v[242:245]
	s_waitcnt lgkmcnt(0)
	v_mfma_f32_16x16x32_bf16 v[4:7], v[4:7], v[174:177], v[0:3]
	v_mfma_f32_16x16x32_bf16 v[0:3], v[196:199], v[226:229], v[154:157]
	v_mfma_f32_16x16x32_bf16 v[18:21], v[200:203], v[222:225], v[18:21]
	v_mfma_f32_16x16x32_bf16 v[0:3], v[200:203], v[174:177], v[0:3]
	v_mfma_f32_16x16x32_bf16 v[26:29], v[246:249], v[82:85], v[26:29]
	v_mfma_f32_16x16x32_bf16 v[30:33], v[214:217], v[82:85], v[30:33]
	v_mfma_f32_16x16x32_bf16 v[82:85], v[250:253], v[166:169], v[26:29]
	v_mfma_f32_16x16x32_bf16 v[26:29], v[214:217], v[170:173], v[158:161]
	v_mfma_f32_16x16x32_bf16 v[54:57], v[218:221], v[204:207], v[26:29]
	v_mfma_f32_16x16x32_bf16 v[26:29], v[246:249], v[170:173], v[162:165]
	v_mfma_f32_16x16x32_bf16 v[8:11], v[246:249], v[208:211], v[8:11]
	v_mfma_f32_16x16x32_bf16 v[50:53], v[250:253], v[204:207], v[26:29]
	v_mfma_f32_16x16x32_bf16 v[12:15], v[214:217], v[208:211], v[12:15]
	v_mfma_f32_16x16x32_bf16 v[26:29], v[250:253], v[222:225], v[8:11]
	v_mfma_f32_16x16x32_bf16 v[8:11], v[214:217], v[226:229], v[178:181]
	v_mfma_f32_16x16x32_bf16 v[98:101], v[218:221], v[166:169], v[30:33]
	v_mfma_f32_16x16x32_bf16 v[30:33], v[218:221], v[222:225], v[12:15]
	v_mfma_f32_16x16x32_bf16 v[12:15], v[218:221], v[174:177], v[8:11]
	v_mfma_f32_16x16x32_bf16 v[8:11], v[246:249], v[226:229], v[182:185]
	v_mfma_f32_16x16x32_bf16 v[8:11], v[250:253], v[174:177], v[8:11]
	s_movk_i32 s1, 0x100
	v_cmp_gt_u32_e32 vcc, s1, v144
	s_barrier
	s_and_saveexec_b64 s[6:7], vcc
	s_cbranch_execz .LBB0_529
	s_barrier

.LBB0_646:
	ds_read_b128 v[144:147], v136
	ds_read_b128 v[148:151], v136 offset:1024
	ds_read_b128 v[152:155], v136 offset:2048
	ds_read_b128 v[156:159], v136 offset:3072
	s_add_i32 s39, s19, s38
	s_add_i32 s61, s39, 0x80080
	s_mov_b32 m0, s13
	ds_read_b128 v[160:163], v137
	ds_read_b128 v[164:167], v137 offset:1024
	ds_read_b128 v[168:171], v138
	ds_read_b128 v[172:175], v138 offset:1024
	ds_read_b128 v[176:179], v139
	ds_read_b128 v[180:183], v139 offset:1024
	ds_read_b128 v[196:199], v140
	ds_read_b128 v[200:203], v140 offset:1024
	buffer_load_dwordx4 v134, s[48:51], s61 offen lds
	s_mov_b32 m0, s12
	s_nop 0
	buffer_load_dwordx4 v135, s[48:51], s61 offen lds
	s_waitcnt lgkmcnt(8)
	s_barrier
	s_waitcnt lgkmcnt(0)
	s_waitcnt lgkmcnt(0)
	v_mfma_f32_16x16x32_bf16 v[126:129], v[144:147], v[160:163], v[126:129]
	v_mfma_f32_16x16x32_bf16 v[122:125], v[152:155], v[160:163], v[122:125]
	v_mfma_f32_16x16x32_bf16 v[118:121], v[144:147], v[168:171], v[118:121]
	v_mfma_f32_16x16x32_bf16 v[114:117], v[152:155], v[168:171], v[114:117]
	v_mfma_f32_16x16x32_bf16 v[110:113], v[144:147], v[176:179], v[110:113]
	v_mfma_f32_16x16x32_bf16 v[106:109], v[152:155], v[176:179], v[106:109]
	v_mfma_f32_16x16x32_bf16 v[102:105], v[144:147], v[196:199], v[102:105]
	v_mfma_f32_16x16x32_bf16 v[98:101], v[152:155], v[196:199], v[98:101]
	v_mfma_f32_16x16x32_bf16 v[126:129], v[148:151], v[164:167], v[126:129]
	v_mfma_f32_16x16x32_bf16 v[122:125], v[156:159], v[164:167], v[122:125]
	v_mfma_f32_16x16x32_bf16 v[118:121], v[148:151], v[172:175], v[118:121]
	v_mfma_f32_16x16x32_bf16 v[114:117], v[156:159], v[172:175], v[114:117]
	v_mfma_f32_16x16x32_bf16 v[110:113], v[148:151], v[180:183], v[110:113]
	v_mfma_f32_16x16x32_bf16 v[106:109], v[156:159], v[180:183], v[106:109]
	v_mfma_f32_16x16x32_bf16 v[102:105], v[148:151], v[200:203], v[102:105]
	v_mfma_f32_16x16x32_bf16 v[98:101], v[156:159], v[200:203], v[98:101]
	s_barrier
	s_add_i32 s61, s20, s38
	s_add_i32 s62, s61, 0x100
	s_mov_b32 m0, s22
	ds_read_b128 v[204:207], v141
	ds_read_b128 v[208:211], v141 offset:1024
	ds_read_b128 v[214:217], v141 offset:2048
	ds_read_b128 v[218:221], v141 offset:3072
	buffer_load_dwordx4 v134, s[52:55], s62 offen lds
	s_mov_b32 m0, s23
	s_nop 0
	buffer_load_dwordx4 v135, s[52:55], s62 offen lds
	s_barrier
	s_waitcnt lgkmcnt(0)
	s_waitcnt lgkmcnt(0)
	v_mfma_f32_16x16x32_bf16 v[94:97], v[204:207], v[160:163], v[94:97]
	v_mfma_f32_16x16x32_bf16 v[90:93], v[214:217], v[160:163], v[90:93]
	v_mfma_f32_16x16x32_bf16 v[86:89], v[204:207], v[168:171], v[86:89]
	v_mfma_f32_16x16x32_bf16 v[82:85], v[214:217], v[168:171], v[82:85]
	v_mfma_f32_16x16x32_bf16 v[78:81], v[204:207], v[176:179], v[78:81]
	v_mfma_f32_16x16x32_bf16 v[74:77], v[214:217], v[176:179], v[74:77]
	v_mfma_f32_16x16x32_bf16 v[70:73], v[204:207], v[196:199], v[70:73]
	v_mfma_f32_16x16x32_bf16 v[66:69], v[214:217], v[196:199], v[66:69]
	v_mfma_f32_16x16x32_bf16 v[94:97], v[208:211], v[164:167], v[94:97]
	v_mfma_f32_16x16x32_bf16 v[90:93], v[218:221], v[164:167], v[90:93]
	v_mfma_f32_16x16x32_bf16 v[86:89], v[208:211], v[172:175], v[86:89]
	v_mfma_f32_16x16x32_bf16 v[82:85], v[218:221], v[172:175], v[82:85]
	v_mfma_f32_16x16x32_bf16 v[78:81], v[208:211], v[180:183], v[78:81]
	v_mfma_f32_16x16x32_bf16 v[74:77], v[218:221], v[180:183], v[74:77]
	v_mfma_f32_16x16x32_bf16 v[70:73], v[208:211], v[200:203], v[70:73]
	v_mfma_f32_16x16x32_bf16 v[66:69], v[218:221], v[200:203], v[66:69]
	s_add_i32 s62, s39, 0x100
	s_mov_b32 m0, s21
	s_barrier
	ds_read_b128 v[160:163], v137 offset:16384
	ds_read_b128 v[164:167], v137 offset:17408
	ds_read_b128 v[168:171], v138 offset:16384
	ds_read_b128 v[172:175], v138 offset:17408
	ds_read_b128 v[176:179], v139 offset:16384
	ds_read_b128 v[180:183], v139 offset:17408
	ds_read_b128 v[196:199], v140 offset:16384
	ds_read_b128 v[200:203], v140 offset:17408
	buffer_load_dwordx4 v134, s[48:51], s62 offen lds
	s_mov_b32 m0, s24
	s_nop 0
	buffer_load_dwordx4 v135, s[48:51], s62 offen lds
	s_barrier
	s_waitcnt lgkmcnt(0)
	s_waitcnt lgkmcnt(0)
	v_mfma_f32_16x16x32_bf16 v[62:65], v[144:147], v[160:163], v[62:65]
	v_mfma_f32_16x16x32_bf16 v[58:61], v[152:155], v[160:163], v[58:61]
	v_mfma_f32_16x16x32_bf16 v[54:57], v[144:147], v[168:171], v[54:57]
	v_mfma_f32_16x16x32_bf16 v[50:53], v[152:155], v[168:171], v[50:53]
	v_mfma_f32_16x16x32_bf16 v[46:49], v[144:147], v[176:179], v[46:49]
	v_mfma_f32_16x16x32_bf16 v[42:45], v[152:155], v[176:179], v[42:45]
	v_mfma_f32_16x16x32_bf16 v[38:41], v[144:147], v[196:199], v[38:41]
	v_mfma_f32_16x16x32_bf16 v[34:37], v[152:155], v[196:199], v[34:37]
	v_mfma_f32_16x16x32_bf16 v[62:65], v[148:151], v[164:167], v[62:65]
	v_mfma_f32_16x16x32_bf16 v[58:61], v[156:159], v[164:167], v[58:61]
	v_mfma_f32_16x16x32_bf16 v[54:57], v[148:151], v[172:175], v[54:57]
	v_mfma_f32_16x16x32_bf16 v[50:53], v[156:159], v[172:175], v[50:53]
	v_mfma_f32_16x16x32_bf16 v[46:49], v[148:151], v[180:183], v[46:49]
	v_mfma_f32_16x16x32_bf16 v[42:45], v[156:159], v[180:183], v[42:45]
	v_mfma_f32_16x16x32_bf16 v[38:41], v[148:151], v[200:203], v[38:41]
	v_mfma_f32_16x16x32_bf16 v[34:37], v[156:159], v[200:203], v[34:37]
	s_barrier
	s_add_i32 s62, s61, 0x80100
	s_mov_b32 m0, s25
	s_nop 0
	buffer_load_dwordx4 v134, s[52:55], s62 offen lds
	s_mov_b32 m0, s26
	s_nop 0
	buffer_load_dwordx4 v135, s[52:55], s62 offen lds
	s_waitcnt vmcnt(6)
	s_barrier
	v_mfma_f32_16x16x32_bf16 v[30:33], v[204:207], v[160:163], v[30:33]
	v_mfma_f32_16x16x32_bf16 v[26:29], v[214:217], v[160:163], v[26:29]
	v_mfma_f32_16x16x32_bf16 v[22:25], v[204:207], v[168:171], v[22:25]
	v_mfma_f32_16x16x32_bf16 v[18:21], v[214:217], v[168:171], v[18:21]
	v_mfma_f32_16x16x32_bf16 v[12:15], v[204:207], v[176:179], v[12:15]
	v_mfma_f32_16x16x32_bf16 v[8:11], v[214:217], v[176:179], v[8:11]
	v_mfma_f32_16x16x32_bf16 v[4:7], v[204:207], v[196:199], v[4:7]
	v_mfma_f32_16x16x32_bf16 v[0:3], v[214:217], v[196:199], v[0:3]
	v_mfma_f32_16x16x32_bf16 v[30:33], v[208:211], v[164:167], v[30:33]
	v_mfma_f32_16x16x32_bf16 v[26:29], v[218:221], v[164:167], v[26:29]
	v_mfma_f32_16x16x32_bf16 v[22:25], v[208:211], v[172:175], v[22:25]
	v_mfma_f32_16x16x32_bf16 v[18:21], v[218:221], v[172:175], v[18:21]
	v_mfma_f32_16x16x32_bf16 v[12:15], v[208:211], v[180:183], v[12:15]
	v_mfma_f32_16x16x32_bf16 v[8:11], v[218:221], v[180:183], v[8:11]
	v_mfma_f32_16x16x32_bf16 v[4:7], v[208:211], v[200:203], v[4:7]
	v_mfma_f32_16x16x32_bf16 v[0:3], v[218:221], v[200:203], v[0:3]
	s_barrier
	ds_read_b128 v[144:147], v142
	ds_read_b128 v[148:151], v142 offset:1024
	ds_read_b128 v[152:155], v142 offset:2048
	ds_read_b128 v[156:159], v142 offset:3072
	s_add_i32 s62, s39, 0x80100
	s_mov_b32 m0, s27
	ds_read_b128 v[160:163], v137 offset:32768
	ds_read_b128 v[164:167], v137 offset:33792
	ds_read_b128 v[168:171], v138 offset:32768
	ds_read_b128 v[172:175], v138 offset:33792
	ds_read_b128 v[176:179], v139 offset:32768
	ds_read_b128 v[180:183], v139 offset:33792
	ds_read_b128 v[196:199], v140 offset:32768
	ds_read_b128 v[200:203], v140 offset:33792
	buffer_load_dwordx4 v134, s[48:51], s62 offen lds
	s_mov_b32 m0, s28
	s_nop 0
	buffer_load_dwordx4 v135, s[48:51], s62 offen lds
	s_waitcnt lgkmcnt(8)
	s_barrier
	s_waitcnt lgkmcnt(0)
	s_waitcnt lgkmcnt(0)
	v_mfma_f32_16x16x32_bf16 v[126:129], v[144:147], v[160:163], v[126:129]
	v_mfma_f32_16x16x32_bf16 v[122:125], v[152:155], v[160:163], v[122:125]
	v_mfma_f32_16x16x32_bf16 v[118:121], v[144:147], v[168:171], v[118:121]
	v_mfma_f32_16x16x32_bf16 v[114:117], v[152:155], v[168:171], v[114:117]
	v_mfma_f32_16x16x32_bf16 v[110:113], v[144:147], v[176:179], v[110:113]
	v_mfma_f32_16x16x32_bf16 v[106:109], v[152:155], v[176:179], v[106:109]
	v_mfma_f32_16x16x32_bf16 v[102:105], v[144:147], v[196:199], v[102:105]
	v_mfma_f32_16x16x32_bf16 v[98:101], v[152:155], v[196:199], v[98:101]
	v_mfma_f32_16x16x32_bf16 v[126:129], v[148:151], v[164:167], v[126:129]
	v_mfma_f32_16x16x32_bf16 v[122:125], v[156:159], v[164:167], v[122:125]
	v_mfma_f32_16x16x32_bf16 v[118:121], v[148:151], v[172:175], v[118:121]
	v_mfma_f32_16x16x32_bf16 v[114:117], v[156:159], v[172:175], v[114:117]
	v_mfma_f32_16x16x32_bf16 v[110:113], v[148:151], v[180:183], v[110:113]
	v_mfma_f32_16x16x32_bf16 v[106:109], v[156:159], v[180:183], v[106:109]
	v_mfma_f32_16x16x32_bf16 v[102:105], v[148:151], v[200:203], v[102:105]
	v_mfma_f32_16x16x32_bf16 v[98:101], v[156:159], v[200:203], v[98:101]
	s_barrier
	s_add_i32 s62, s61, 0x180
	s_mov_b32 m0, s29
	ds_read_b128 v[204:207], v143
	ds_read_b128 v[208:211], v143 offset:1024
	ds_read_b128 v[214:217], v143 offset:2048
	ds_read_b128 v[218:221], v143 offset:3072
	buffer_load_dwordx4 v134, s[52:55], s62 offen lds
	s_mov_b32 m0, s30
	s_nop 0
	buffer_load_dwordx4 v135, s[52:55], s62 offen lds
	s_barrier
	s_waitcnt lgkmcnt(0)
	s_waitcnt lgkmcnt(0)
	v_mfma_f32_16x16x32_bf16 v[94:97], v[204:207], v[160:163], v[94:97]
	v_mfma_f32_16x16x32_bf16 v[90:93], v[214:217], v[160:163], v[90:93]
	v_mfma_f32_16x16x32_bf16 v[86:89], v[204:207], v[168:171], v[86:89]
	v_mfma_f32_16x16x32_bf16 v[82:85], v[214:217], v[168:171], v[82:85]
	v_mfma_f32_16x16x32_bf16 v[78:81], v[204:207], v[176:179], v[78:81]
	v_mfma_f32_16x16x32_bf16 v[74:77], v[214:217], v[176:179], v[74:77]
	v_mfma_f32_16x16x32_bf16 v[70:73], v[204:207], v[196:199], v[70:73]
	v_mfma_f32_16x16x32_bf16 v[66:69], v[214:217], v[196:199], v[66:69]
	v_mfma_f32_16x16x32_bf16 v[94:97], v[208:211], v[164:167], v[94:97]
	v_mfma_f32_16x16x32_bf16 v[90:93], v[218:221], v[164:167], v[90:93]
	v_mfma_f32_16x16x32_bf16 v[86:89], v[208:211], v[172:175], v[86:89]
	v_mfma_f32_16x16x32_bf16 v[82:85], v[218:221], v[172:175], v[82:85]
	v_mfma_f32_16x16x32_bf16 v[78:81], v[208:211], v[180:183], v[78:81]
	v_mfma_f32_16x16x32_bf16 v[74:77], v[218:221], v[180:183], v[74:77]
	v_mfma_f32_16x16x32_bf16 v[70:73], v[208:211], v[200:203], v[70:73]
	v_mfma_f32_16x16x32_bf16 v[66:69], v[218:221], v[200:203], v[66:69]
	s_addk_i32 s39, 0x180
	s_mov_b32 m0, s31
	s_barrier
	ds_read_b128 v[160:163], v137 offset:49152
	ds_read_b128 v[164:167], v137 offset:50176
	ds_read_b128 v[168:171], v138 offset:49152
	ds_read_b128 v[172:175], v138 offset:50176
	ds_read_b128 v[176:179], v139 offset:49152
	ds_read_b128 v[180:183], v139 offset:50176
	ds_read_b128 v[196:199], v140 offset:49152
	ds_read_b128 v[200:203], v140 offset:50176
	buffer_load_dwordx4 v134, s[48:51], s39 offen lds
	s_mov_b32 m0, s34
	s_nop 0
	buffer_load_dwordx4 v135, s[48:51], s39 offen lds
	s_barrier
	s_waitcnt lgkmcnt(0)
	s_waitcnt lgkmcnt(0)
	v_mfma_f32_16x16x32_bf16 v[62:65], v[144:147], v[160:163], v[62:65]
	v_mfma_f32_16x16x32_bf16 v[58:61], v[152:155], v[160:163], v[58:61]
	v_mfma_f32_16x16x32_bf16 v[54:57], v[144:147], v[168:171], v[54:57]
	v_mfma_f32_16x16x32_bf16 v[50:53], v[152:155], v[168:171], v[50:53]
	v_mfma_f32_16x16x32_bf16 v[46:49], v[144:147], v[176:179], v[46:49]
	v_mfma_f32_16x16x32_bf16 v[42:45], v[152:155], v[176:179], v[42:45]
	v_mfma_f32_16x16x32_bf16 v[38:41], v[144:147], v[196:199], v[38:41]
	v_mfma_f32_16x16x32_bf16 v[34:37], v[152:155], v[196:199], v[34:37]
	v_mfma_f32_16x16x32_bf16 v[62:65], v[148:151], v[164:167], v[62:65]
	v_mfma_f32_16x16x32_bf16 v[58:61], v[156:159], v[164:167], v[58:61]
	v_mfma_f32_16x16x32_bf16 v[54:57], v[148:151], v[172:175], v[54:57]
	v_mfma_f32_16x16x32_bf16 v[50:53], v[156:159], v[172:175], v[50:53]
	v_mfma_f32_16x16x32_bf16 v[46:49], v[148:151], v[180:183], v[46:49]
	v_mfma_f32_16x16x32_bf16 v[42:45], v[156:159], v[180:183], v[42:45]
	v_mfma_f32_16x16x32_bf16 v[38:41], v[148:151], v[200:203], v[38:41]
	v_mfma_f32_16x16x32_bf16 v[34:37], v[156:159], v[200:203], v[34:37]
	s_barrier
	s_add_i32 s61, s61, 0x80180
	s_mov_b32 m0, s35
	s_nop 0
	buffer_load_dwordx4 v134, s[52:55], s61 offen lds
	s_mov_b32 m0, s36
	s_nop 0
	buffer_load_dwordx4 v135, s[52:55], s61 offen lds
	s_waitcnt vmcnt(6)
	s_barrier
	v_mfma_f32_16x16x32_bf16 v[30:33], v[204:207], v[160:163], v[30:33]
	v_mfma_f32_16x16x32_bf16 v[26:29], v[214:217], v[160:163], v[26:29]
	v_mfma_f32_16x16x32_bf16 v[22:25], v[204:207], v[168:171], v[22:25]
	v_mfma_f32_16x16x32_bf16 v[18:21], v[214:217], v[168:171], v[18:21]
	v_mfma_f32_16x16x32_bf16 v[12:15], v[204:207], v[176:179], v[12:15]
	v_mfma_f32_16x16x32_bf16 v[8:11], v[214:217], v[176:179], v[8:11]
	v_mfma_f32_16x16x32_bf16 v[4:7], v[204:207], v[196:199], v[4:7]
	v_mfma_f32_16x16x32_bf16 v[0:3], v[214:217], v[196:199], v[0:3]
	v_mfma_f32_16x16x32_bf16 v[30:33], v[208:211], v[164:167], v[30:33]
	v_mfma_f32_16x16x32_bf16 v[26:29], v[218:221], v[164:167], v[26:29]
	v_mfma_f32_16x16x32_bf16 v[22:25], v[208:211], v[172:175], v[22:25]
	v_mfma_f32_16x16x32_bf16 v[18:21], v[218:221], v[172:175], v[18:21]
	v_mfma_f32_16x16x32_bf16 v[12:15], v[208:211], v[180:183], v[12:15]
	v_mfma_f32_16x16x32_bf16 v[8:11], v[218:221], v[180:183], v[8:11]
	v_mfma_f32_16x16x32_bf16 v[4:7], v[208:211], v[200:203], v[4:7]
	v_mfma_f32_16x16x32_bf16 v[0:3], v[218:221], v[200:203], v[0:3]
	s_add_i32 s37, s37, 2
	s_addk_i32 s38, 0x100
	s_cmp_lt_u32 s37, 28
	s_barrier
	s_cbranch_scc1 .LBB0_646
	v_mov_b32_e32 v144, v130
	s_or_b32 s19, s19, 0x80f80
	v_and_b32_e32 v147, 15, v144
	v_bfe_u32 v146, v144, 4, 2
	v_lshlrev_b32_e32 v150, 2, v144
	v_bfe_u32 v145, v144, 6, 2
	v_lshlrev_b32_e32 v174, 4, v146
	v_lshlrev_b32_e32 v148, 6, v147
	v_and_b32_e32 v175, 32, v150
	v_lshlrev_b32_e32 v149, 12, v145
	v_bitop3_b32 v190, v174, v175, v148 bitop3:0x36
	v_add3_u32 v148, s78, v190, v149
	ds_read_b128 v[150:153], v148
	ds_read_b128 v[154:157], v148 offset:1024
	ds_read_b128 v[158:161], v148 offset:2048
	ds_read_b128 v[162:165], v148 offset:3072
	v_ashrrev_i32_e32 v148, 2, v144
	v_lshlrev_b32_e32 v177, 6, v144
	v_and_b32_e32 v148, 0xffffffc0, v148
	v_and_b32_e32 v177, 0x3c0, v177
	v_lshlrev_b32_e32 v176, 7, v148
	v_bitop3_b32 v174, v177, v175, v174 bitop3:0x36
	s_waitcnt vmcnt(0)
	v_add3_u32 v250, 0, v190, v176
	v_add3_u32 v251, 0, v174, v176
	s_mov_b32 m0, s13
	ds_read_b128 v[166:169], v250
	ds_read_b128 v[170:173], v250 offset:1024
	ds_read_b128 v[174:177], v251 offset:2048
	ds_read_b128 v[178:181], v251 offset:3072
	ds_read_b128 v[182:185], v251 offset:4096
	ds_read_b128 v[196:199], v251 offset:5120
	ds_read_b128 v[200:203], v251 offset:6144
	ds_read_b128 v[204:207], v251 offset:7168
	buffer_load_dwordx4 v134, s[48:51], s19 offen lds
	s_mov_b32 m0, s12
	s_nop 0
	buffer_load_dwordx4 v135, s[48:51], s19 offen lds
	s_barrier
	s_waitcnt lgkmcnt(0)
	s_waitcnt lgkmcnt(0)
	v_mfma_f32_16x16x32_bf16 v[126:129], v[150:153], v[166:169], v[126:129]
	v_mfma_f32_16x16x32_bf16 v[122:125], v[158:161], v[166:169], v[122:125]
	v_mfma_f32_16x16x32_bf16 v[118:121], v[150:153], v[174:177], v[118:121]
	v_mfma_f32_16x16x32_bf16 v[114:117], v[158:161], v[174:177], v[114:117]
	v_mfma_f32_16x16x32_bf16 v[102:105], v[150:153], v[200:203], v[102:105]
	v_mfma_f32_16x16x32_bf16 v[98:101], v[158:161], v[200:203], v[98:101]
	v_mfma_f32_16x16x32_bf16 v[126:129], v[154:157], v[170:173], v[126:129]
	v_mfma_f32_16x16x32_bf16 v[122:125], v[162:165], v[170:173], v[122:125]
	v_mfma_f32_16x16x32_bf16 v[118:121], v[154:157], v[178:181], v[118:121]
	v_mfma_f32_16x16x32_bf16 v[114:117], v[162:165], v[178:181], v[114:117]
	v_mfma_f32_16x16x32_bf16 v[110:113], v[150:153], v[182:185], v[110:113]
	v_mfma_f32_16x16x32_bf16 v[106:109], v[158:161], v[182:185], v[106:109]
	v_mfma_f32_16x16x32_bf16 v[102:105], v[154:157], v[204:207], v[102:105]
	v_mfma_f32_16x16x32_bf16 v[98:101], v[162:165], v[204:207], v[98:101]
	v_mfma_f32_16x16x32_bf16 v[208:211], v[154:157], v[196:199], v[110:113]
	v_mfma_f32_16x16x32_bf16 v[214:217], v[162:165], v[196:199], v[106:109]
	v_add3_u32 v222, s77, v190, v149
	s_barrier
	s_nop 0
	ds_read_b128 v[106:109], v222
	ds_read_b128 v[110:113], v222 offset:1024
	ds_read_b128 v[218:221], v222 offset:2048
	ds_read_b128 v[222:225], v222 offset:3072
	s_barrier
	s_waitcnt lgkmcnt(0)
	s_waitcnt lgkmcnt(0)
	v_mfma_f32_16x16x32_bf16 v[94:97], v[106:109], v[166:169], v[94:97]
	v_mfma_f32_16x16x32_bf16 v[82:85], v[218:221], v[174:177], v[82:85]
	v_mfma_f32_16x16x32_bf16 v[78:81], v[106:109], v[182:185], v[78:81]
	v_mfma_f32_16x16x32_bf16 v[74:77], v[218:221], v[182:185], v[74:77]
	v_mfma_f32_16x16x32_bf16 v[70:73], v[106:109], v[200:203], v[70:73]
	v_mfma_f32_16x16x32_bf16 v[66:69], v[218:221], v[200:203], v[66:69]
	v_mfma_f32_16x16x32_bf16 v[94:97], v[110:113], v[170:173], v[94:97]
	v_mfma_f32_16x16x32_bf16 v[90:93], v[218:221], v[166:169], v[90:93]
	v_mfma_f32_16x16x32_bf16 v[86:89], v[106:109], v[174:177], v[86:89]
	v_mfma_f32_16x16x32_bf16 v[82:85], v[222:225], v[178:181], v[82:85]
	v_mfma_f32_16x16x32_bf16 v[78:81], v[110:113], v[196:199], v[78:81]
	v_mfma_f32_16x16x32_bf16 v[74:77], v[222:225], v[196:199], v[74:77]
	v_mfma_f32_16x16x32_bf16 v[70:73], v[110:113], v[204:207], v[70:73]
	v_mfma_f32_16x16x32_bf16 v[66:69], v[222:225], v[204:207], v[66:69]
	v_mfma_f32_16x16x32_bf16 v[166:169], v[222:225], v[170:173], v[90:93]
	v_mfma_f32_16x16x32_bf16 v[170:173], v[110:113], v[178:181], v[86:89]
	s_barrier
	s_nop 0
	ds_read_b128 v[86:89], v250 offset:16384
	ds_read_b128 v[90:93], v250 offset:17408
	ds_read_b128 v[174:177], v251 offset:18432
	ds_read_b128 v[178:181], v251 offset:19456
	ds_read_b128 v[182:185], v251 offset:20480
	ds_read_b128 v[196:199], v251 offset:21504
	ds_read_b128 v[200:203], v251 offset:22528
	ds_read_b128 v[204:207], v251 offset:23552
	s_waitcnt vmcnt(4)
	s_barrier
	s_waitcnt lgkmcnt(0)
	s_waitcnt lgkmcnt(0)
	v_mfma_f32_16x16x32_bf16 v[54:57], v[150:153], v[174:177], v[54:57]
	v_mfma_f32_16x16x32_bf16 v[50:53], v[158:161], v[174:177], v[50:53]
	v_mfma_f32_16x16x32_bf16 v[62:65], v[150:153], v[86:89], v[62:65]
	v_mfma_f32_16x16x32_bf16 v[58:61], v[158:161], v[86:89], v[58:61]
	v_mfma_f32_16x16x32_bf16 v[54:57], v[154:157], v[178:181], v[54:57]
	v_mfma_f32_16x16x32_bf16 v[50:53], v[162:165], v[178:181], v[50:53]
	v_mfma_f32_16x16x32_bf16 v[46:49], v[150:153], v[182:185], v[46:49]
	v_mfma_f32_16x16x32_bf16 v[42:45], v[158:161], v[182:185], v[42:45]
	v_mfma_f32_16x16x32_bf16 v[38:41], v[150:153], v[200:203], v[38:41]
	v_mfma_f32_16x16x32_bf16 v[34:37], v[158:161], v[200:203], v[34:37]
	v_mfma_f32_16x16x32_bf16 v[226:229], v[154:157], v[90:93], v[62:65]
	v_mfma_f32_16x16x32_bf16 v[230:233], v[162:165], v[90:93], v[58:61]
	v_mfma_f32_16x16x32_bf16 v[234:237], v[154:157], v[196:199], v[46:49]
	v_mfma_f32_16x16x32_bf16 v[238:241], v[162:165], v[196:199], v[42:45]
	v_mfma_f32_16x16x32_bf16 v[150:153], v[154:157], v[204:207], v[38:41]
	v_mfma_f32_16x16x32_bf16 v[154:157], v[162:165], v[204:207], v[34:37]
	v_mfma_f32_16x16x32_bf16 v[30:33], v[106:109], v[86:89], v[30:33]
	v_mfma_f32_16x16x32_bf16 v[26:29], v[218:221], v[86:89], v[26:29]
	v_mfma_f32_16x16x32_bf16 v[12:15], v[106:109], v[182:185], v[12:15]
	v_mfma_f32_16x16x32_bf16 v[8:11], v[218:221], v[182:185], v[8:11]
	v_mfma_f32_16x16x32_bf16 v[30:33], v[110:113], v[90:93], v[30:33]
	v_mfma_f32_16x16x32_bf16 v[26:29], v[222:225], v[90:93], v[26:29]
	v_mfma_f32_16x16x32_bf16 v[22:25], v[106:109], v[174:177], v[22:25]
	v_mfma_f32_16x16x32_bf16 v[18:21], v[218:221], v[174:177], v[18:21]
	v_mfma_f32_16x16x32_bf16 v[12:15], v[110:113], v[196:199], v[12:15]
	v_mfma_f32_16x16x32_bf16 v[8:11], v[222:225], v[196:199], v[8:11]
	v_mfma_f32_16x16x32_bf16 v[4:7], v[106:109], v[200:203], v[4:7]
	v_mfma_f32_16x16x32_bf16 v[0:3], v[218:221], v[200:203], v[0:3]
	v_mfma_f32_16x16x32_bf16 v[158:161], v[110:113], v[178:181], v[22:25]
	v_mfma_f32_16x16x32_bf16 v[162:165], v[222:225], v[178:181], v[18:21]
	v_mfma_f32_16x16x32_bf16 v[174:177], v[110:113], v[204:207], v[4:7]
	v_mfma_f32_16x16x32_bf16 v[178:181], v[222:225], v[204:207], v[0:3]
	v_add3_u32 v18, s2, v190, v149
	s_barrier
	s_nop 0
	ds_read_b128 v[0:3], v18
	ds_read_b128 v[4:7], v18 offset:1024
	ds_read_b128 v[182:185], v18 offset:2048
	ds_read_b128 v[196:199], v18 offset:3072
	ds_read_b128 v[18:21], v250 offset:32768
	ds_read_b128 v[22:25], v250 offset:33792
	ds_read_b128 v[42:45], v251 offset:34816
	ds_read_b128 v[46:49], v251 offset:35840
	ds_read_b128 v[200:203], v251 offset:36864
	ds_read_b128 v[204:207], v251 offset:37888
	ds_read_b128 v[218:221], v251 offset:38912
	ds_read_b128 v[222:225], v251 offset:39936
	s_waitcnt vmcnt(2)
	s_barrier
	s_waitcnt lgkmcnt(0)
	s_waitcnt lgkmcnt(0)
	v_mfma_f32_16x16x32_bf16 v[34:37], v[0:3], v[18:21], v[126:129]
	v_mfma_f32_16x16x32_bf16 v[110:113], v[4:7], v[22:25], v[34:37]
	v_mfma_f32_16x16x32_bf16 v[34:37], v[182:185], v[18:21], v[122:125]
	v_mfma_f32_16x16x32_bf16 v[106:109], v[196:199], v[22:25], v[34:37]
	v_mfma_f32_16x16x32_bf16 v[34:37], v[0:3], v[42:45], v[118:121]
	v_mfma_f32_16x16x32_bf16 v[90:93], v[4:7], v[46:49], v[34:37]
	v_mfma_f32_16x16x32_bf16 v[34:37], v[182:185], v[42:45], v[114:117]
	v_mfma_f32_16x16x32_bf16 v[86:89], v[196:199], v[46:49], v[34:37]
	v_mfma_f32_16x16x32_bf16 v[34:37], v[0:3], v[200:203], v[208:211]
	v_mfma_f32_16x16x32_bf16 v[62:65], v[4:7], v[204:207], v[34:37]
	v_mfma_f32_16x16x32_bf16 v[34:37], v[182:185], v[200:203], v[214:217]
	v_mfma_f32_16x16x32_bf16 v[58:61], v[196:199], v[204:207], v[34:37]
	v_mfma_f32_16x16x32_bf16 v[34:37], v[0:3], v[218:221], v[102:105]
	v_mfma_f32_16x16x32_bf16 v[38:41], v[4:7], v[222:225], v[34:37]
	v_mfma_f32_16x16x32_bf16 v[34:37], v[182:185], v[218:221], v[98:101]
	v_mfma_f32_16x16x32_bf16 v[34:37], v[196:199], v[222:225], v[34:37]
	s_nop 0
	v_add3_u32 v98, s91, v190, v149
	s_barrier
	ds_read_b128 v[208:211], v98
	ds_read_b128 v[214:217], v98 offset:1024
	ds_read_b128 v[242:245], v98 offset:2048
	ds_read_b128 v[246:249], v98 offset:3072
	s_waitcnt vmcnt(0)
	s_barrier
	s_waitcnt lgkmcnt(0)
	s_waitcnt lgkmcnt(0)
	v_mfma_f32_16x16x32_bf16 v[94:97], v[208:211], v[18:21], v[94:97]
	v_mfma_f32_16x16x32_bf16 v[18:21], v[242:245], v[18:21], v[166:169]
	v_mfma_f32_16x16x32_bf16 v[122:125], v[246:249], v[22:25], v[18:21]
	v_mfma_f32_16x16x32_bf16 v[18:21], v[208:211], v[42:45], v[170:173]
	v_mfma_f32_16x16x32_bf16 v[118:121], v[214:217], v[46:49], v[18:21]
	v_mfma_f32_16x16x32_bf16 v[18:21], v[242:245], v[42:45], v[82:85]
	v_mfma_f32_16x16x32_bf16 v[114:117], v[246:249], v[46:49], v[18:21]
	v_mfma_f32_16x16x32_bf16 v[18:21], v[208:211], v[200:203], v[78:81]
	v_mfma_f32_16x16x32_bf16 v[102:105], v[214:217], v[204:207], v[18:21]
	v_mfma_f32_16x16x32_bf16 v[18:21], v[242:245], v[200:203], v[74:77]
	v_mfma_f32_16x16x32_bf16 v[126:129], v[214:217], v[22:25], v[94:97]
	v_mfma_f32_16x16x32_bf16 v[94:97], v[246:249], v[204:207], v[18:21]
	v_mfma_f32_16x16x32_bf16 v[18:21], v[208:211], v[218:221], v[70:73]
	v_mfma_f32_16x16x32_bf16 v[70:73], v[214:217], v[222:225], v[18:21]
	v_mfma_f32_16x16x32_bf16 v[18:21], v[242:245], v[218:221], v[66:69]
	v_mfma_f32_16x16x32_bf16 v[66:69], v[246:249], v[222:225], v[18:21]
	s_barrier
	ds_read_b128 v[82:85], v250 offset:49152
	ds_read_b128 v[166:169], v250 offset:50176
	ds_read_b128 v[170:173], v251 offset:51200
	ds_read_b128 v[200:203], v251 offset:52224
	ds_read_b128 v[204:207], v251 offset:53248
	ds_read_b128 v[218:221], v251 offset:54272
	ds_read_b128 v[222:225], v251 offset:55296
	ds_read_b128 v[250:253], v251 offset:56320
	s_barrier
	s_waitcnt lgkmcnt(0)
	s_waitcnt lgkmcnt(0)
	v_mfma_f32_16x16x32_bf16 v[18:21], v[0:3], v[82:85], v[226:229]
	v_mfma_f32_16x16x32_bf16 v[78:81], v[4:7], v[166:169], v[18:21]
	v_mfma_f32_16x16x32_bf16 v[18:21], v[182:185], v[82:85], v[230:233]
	v_mfma_f32_16x16x32_bf16 v[74:77], v[196:199], v[166:169], v[18:21]
	v_mfma_f32_16x16x32_bf16 v[18:21], v[0:3], v[170:173], v[54:57]
	v_mfma_f32_16x16x32_bf16 v[46:49], v[4:7], v[200:203], v[18:21]
	v_mfma_f32_16x16x32_bf16 v[18:21], v[182:185], v[170:173], v[50:53]
	v_mfma_f32_16x16x32_bf16 v[42:45], v[196:199], v[200:203], v[18:21]
	v_mfma_f32_16x16x32_bf16 v[18:21], v[0:3], v[204:207], v[234:237]
	v_mfma_f32_16x16x32_bf16 v[0:3], v[0:3], v[222:225], v[150:153]
	v_mfma_f32_16x16x32_bf16 v[22:25], v[4:7], v[218:221], v[18:21]
	v_mfma_f32_16x16x32_bf16 v[18:21], v[182:185], v[204:207], v[238:241]
	v_mfma_f32_16x16x32_bf16 v[4:7], v[4:7], v[250:253], v[0:3]
	v_mfma_f32_16x16x32_bf16 v[0:3], v[182:185], v[222:225], v[154:157]
	v_mfma_f32_16x16x32_bf16 v[18:21], v[196:199], v[218:221], v[18:21]
	v_mfma_f32_16x16x32_bf16 v[0:3], v[196:199], v[250:253], v[0:3]
	v_mfma_f32_16x16x32_bf16 v[26:29], v[242:245], v[82:85], v[26:29]
	v_mfma_f32_16x16x32_bf16 v[30:33], v[208:211], v[82:85], v[30:33]
	v_mfma_f32_16x16x32_bf16 v[82:85], v[246:249], v[166:169], v[26:29]
	v_mfma_f32_16x16x32_bf16 v[26:29], v[208:211], v[170:173], v[158:161]
	v_mfma_f32_16x16x32_bf16 v[54:57], v[214:217], v[200:203], v[26:29]
	v_mfma_f32_16x16x32_bf16 v[26:29], v[242:245], v[170:173], v[162:165]
	v_mfma_f32_16x16x32_bf16 v[8:11], v[242:245], v[204:207], v[8:11]
	v_mfma_f32_16x16x32_bf16 v[50:53], v[246:249], v[200:203], v[26:29]
	v_mfma_f32_16x16x32_bf16 v[12:15], v[208:211], v[204:207], v[12:15]
	v_mfma_f32_16x16x32_bf16 v[26:29], v[246:249], v[218:221], v[8:11]
	v_mfma_f32_16x16x32_bf16 v[8:11], v[208:211], v[222:225], v[174:177]
	v_mfma_f32_16x16x32_bf16 v[98:101], v[214:217], v[166:169], v[30:33]
	v_mfma_f32_16x16x32_bf16 v[30:33], v[214:217], v[218:221], v[12:15]
	v_mfma_f32_16x16x32_bf16 v[12:15], v[214:217], v[250:253], v[8:11]
	v_mfma_f32_16x16x32_bf16 v[8:11], v[242:245], v[222:225], v[178:181]
	v_mfma_f32_16x16x32_bf16 v[8:11], v[246:249], v[250:253], v[8:11]
	s_movk_i32 s1, 0x100
	v_cmp_gt_u32_e32 vcc, s1, v144
	s_barrier
	s_and_saveexec_b64 s[12:13], vcc
	s_cbranch_execz .LBB0_649
	s_barrier
